# attention loops: the packed v_pk_add_f32 row-sum adds split into two plain v_add_f32 each (same order, bit-identical)
# baseline (speedup 1.0000x reference)
; #define LASP __attribute__((address_space(3)))
; template <int DQK>
; __device__ __forceinline__ void flash_item(unsigned char* smem, const bf16_t* Q, int qs, const bf16_t* K0, const bf16_t* V0, int n0, const bf16_t* K1, const bf16_t* V1, int n1, int ks, int vs, bf16_t* Oo, int os, float shift) {
;     ...
;         for (int kk = 0; kk < NKK; ++kk) qf[qg][kk] = *(const bf16x8_t*)(Q + (size_t)(wave * 32 + qg * 16 + fr) * qs + kk * 32 + fq * 8);
;     f32x4_t o[4][2];
; #pragma unroll
;     for (int dg = 0; dg < 4; ++dg) { o[dg][0] = (f32x4_t){0.f, 0.f, 0.f, 0.f}; o[dg][1] = (f32x4_t){0.f, 0.f, 0.f, 0.f}; }
;     float lsum[2] = {0.f, 0.f};
;     const float nsh = -shift;
;     const int ntiles = (n0 + n1) / KT;
;     u32x4_t kreg[NKC], vreg[NVC];
;     ...
;     FL_LOAD(0);
;     for (int t = 0; t < ntiles; ++t) {
;         __syncthreads();
; #pragma unroll
;         for (int c = 0; c < NKC; ++c) *(LASP u32x4_t*)(ls + (tid >> 2) * KR + ((tid & 3) + 4 * c) * 16) = kreg[c];
; #pragma unroll
;         for (int c = 0; c < NVC; ++c) *(LASP u32x4_t*)(ls + VOFF + ((tid >> 3) + 64 * c) * VR + (tid & 7) * 16) = vreg[c];
;         __syncthreads();
;         f32x4_t s[NKG][2];
; #pragma unroll
;         for (int kg = 0; kg < NKG; ++kg) { s[kg][0] = (f32x4_t){nsh, nsh, nsh, nsh}; s[kg][1] = (f32x4_t){nsh, nsh, nsh, nsh}; }
; #pragma unroll
;         for (int kk = 0; kk < NKK; ++kk) {
; #pragma unroll
;             for (int kg = 0; kg < NKG; ++kg) {
;                 const bf16x8_t kf = *(const LASP bf16x8_t*)(ls + (kg * 16 + fr) * KR + (kk * 32 + fq * 8) * 2);
; __device__ __forceinline__ void p4_attn(const Params& P, int l, bool last, unsigned char* smem) {
;     ...
;                 const bf16_t* MQ = (const bf16_t*)(ws + WS_MQ); const bf16_t* MK = (const bf16_t*)(ws + WS_MK); const bf16_t* MV = (const bf16_t*)(ws + WS_MV);
;                 const bool lat = i < 96;
;                 const int bh = q * 12 + (lat ? (i >> 3) : (i - 192)), b = bh / 6, h = bh % 6;
;                 const size_t c0 = (size_t)NLAT + b * CTXL, l0 = (size_t)b * SEQ;
;                 const size_t q0 = lat ? l0 + (i & 7) * 256 : c0;
;                 flash_item<96>(smem, MQ + q0 * 576 + h * 96, 576, MK + c0 * 576 + h * 96, MV + c0 * 384 + h * 64, CTXL, MK + l0 * 576 + h * 96, MV + l0 * 384 + h * 64, lat ? SEQ : 0, 576, 384,
;                                O + q0 * OW + 384 + h * 64, OW, shift_mla);
.Lprio_mla_skip:
	s_ashr_i32 s2, s13, 3
	s_add_i32 s3, s13, 0xffffff40
	s_cmpk_lt_i32 s13, 0x60
	s_cselect_b32 s2, s2, s3
	s_cselect_b32 s27, 18, 2
	s_add_i32 s5, s2, s10
	s_mul_hi_i32 s2, s5, 0x2aaaaaab
	s_lshr_b32 s3, s2, 31
	s_add_i32 s2, s2, s3
	s_lshl_b32 s3, s2, 8
	s_ashr_i32 s16, s3, 31
	s_add_u32 s20, s3, 0x8000
	s_addc_u32 s21, s16, 0
	s_ashr_i32 s3, s2, 31
	s_lshl_b64 s[16:17], s[2:3], 11
	s_lshl_b32 s3, s13, 8
	s_and_b32 s3, s3, 0x700
	s_or_b32 s3, s16, s3
	s_cmpk_lt_i32 s13, 0x60
	s_mul_i32 s16, s2, 6
	s_cselect_b32 s28, s17, s21
	s_cselect_b32 s3, s3, s20
	s_sub_i32 s5, s5, s16
	s_mul_i32 s16, s28, 0x480
	s_mul_hi_u32 s17, s3, 0x480
	s_add_i32 s17, s17, s16
	s_mul_i32 s18, s3, 0x480
	s_mul_i32 s16, s5, 0x60
	s_add_u32 s18, s59, s18
	s_addc_u32 s19, s80, s17
	s_ashr_i32 s17, s16, 31
	s_lshl_b64 s[16:17], s[16:17], 1
	s_mul_hi_u32 s29, s20, 0x480
	s_mul_i32 s38, s21, 0x480
	s_add_u32 s18, s18, s16
	s_addc_u32 s19, s19, s17
	s_add_i32 s29, s29, s38
	s_mul_i32 s38, s20, 0x480
	s_add_u32 s38, s70, s38
	s_addc_u32 s29, s71, s29
	s_mul_hi_u32 s40, s20, 0x300
	s_mulk_i32 s21, 0x300
	s_add_u32 s38, s38, s16
	s_addc_u32 s39, s29, s17
	s_add_i32 s40, s40, s21
	s_mulk_i32 s20, 0x300
	s_add_u32 s29, s81, s20
	s_addc_u32 s41, s82, s40
	s_lshl_b32 s20, s5, 6
	s_ashr_i32 s21, s20, 31
	v_mov_b32_e32 v126, v253
	s_lshl_b64 s[20:21], s[20:21], 1
	v_lshlrev_b32_e32 v1, 3, v126
	s_add_u32 s40, s29, s20
	v_ashrrev_i32_e32 v127, 2, v126
	s_waitcnt vmcnt(8)
	v_and_b32_e32 v55, 24, v1
	v_lshlrev_b32_e32 v1, 4, v126
	v_mov_b64_e32 v[2:3], s[38:39]
	s_addc_u32 s41, s41, s21
	v_ashrrev_i32_e32 v129, 3, v126
	v_and_b32_e32 v22, 0x70, v1
	v_mov_b32_e32 v23, v0
	v_mad_i64_i32 v[2:3], s[38:39], v127, s91, v[2:3]
	v_lshlrev_b32_e32 v4, 1, v55
	v_mov_b32_e32 v5, v0
	v_add_u32_e32 v54, 64, v129
	v_lshl_add_u64 v[50:51], s[40:41], 0, v[22:23]
	v_lshl_add_u64 v[52:53], v[2:3], 0, v[4:5]
	v_mad_i64_i32 v[14:15], s[40:41], v54, s87, v[50:51]
	global_load_dwordx4 v[2:5], v[52:53], off offset:64
	global_load_dwordx4 v[6:9], v[52:53], off
	v_mad_i64_i32 v[16:17], s[38:39], v129, s87, v[50:51]
	global_load_dwordx4 v[10:13], v[52:53], off offset:128
	global_load_dwordx4 v[38:41], v[16:17], off
	global_load_dwordx4 v[42:45], v[14:15], off
	v_and_b32_e32 v130, 15, v126
	v_ashrrev_i32_e32 v14, 1, v126
	v_bfe_u32 v120, v126, 4, 2
	v_and_or_b32 v144, v14, s95, v130
	v_lshlrev_b32_e32 v24, 4, v120
	v_mov_b32_e32 v25, v0
	v_lshl_add_u64 v[18:19], s[18:19], 0, v[24:25]
	v_or_b32_e32 v142, 16, v144
	v_mad_i64_i32 v[34:35], s[18:19], v144, s91, v[18:19]
	v_mad_i64_i32 v[30:31], s[18:19], v142, s91, v[18:19]
	global_load_dwordx4 v[14:17], v[34:35], off
	global_load_dwordx4 v[18:21], v[30:31], off
	v_mul_lo_u32 v23, v127, s96
	v_and_b32_e32 v1, 48, v1
	v_mul_lo_u32 v25, v129, s89
	v_add_u32_e32 v23, 0, v23
	v_add_u32_e32 v22, 0, v22
	v_add_u32_e32 v128, 0, v24
	v_add_u32_e32 v1, v23, v1
	v_add_u32_e32 v143, v22, v25
	global_load_dwordx4 v[22:25], v[34:35], off offset:64
	global_load_dwordx4 v[26:29], v[30:31], off offset:128
	s_nop 0
	global_load_dwordx4 v[30:33], v[30:31], off offset:64
	s_nop 0
	global_load_dwordx4 v[34:37], v[34:35], off offset:128
	v_mad_u32_u24 v121, v130, s96, v128
	s_barrier
	v_lshlrev_b32_e32 v145, 2, v120
	v_add_u32_e32 v131, 0, v55
	s_mov_b32 s5, 0x24000
	s_mul_i32 s38, s2, 0x240000
	s_mov_b32 s29, 1
	s_waitcnt vmcnt(9)
	ds_write_b128 v1, v[6:9]
	ds_write_b128 v1, v[2:5] offset:64
	s_waitcnt vmcnt(8)
	ds_write_b128 v1, v[10:13] offset:128
	s_waitcnt vmcnt(7)
	ds_write_b128 v143, v[38:41] offset:32768
	s_waitcnt vmcnt(6)
	ds_write_b128 v143, v[42:45] offset:41984
	s_waitcnt lgkmcnt(0)
	s_barrier
	ds_read_b128 v[2:5], v121
	ds_read_b128 v[10:13], v121 offset:3328
	ds_read_b128 v[46:49], v121 offset:6656
	ds_read_b128 v[56:59], v121 offset:9984
	ds_read_b128 v[68:71], v121 offset:13312
	ds_read_b128 v[72:75], v121 offset:16640
	ds_read_b128 v[84:87], v121 offset:19968
	ds_read_b128 v[88:91], v121 offset:23296
	v_mov_b64_e32 v[6:7], s[44:45]
	v_mov_b64_e32 v[8:9], s[46:47]
	s_waitcnt vmcnt(5) lgkmcnt(7)
	s_nop 0
	v_mfma_f32_16x16x32_bf16 v[38:41], v[2:5], v[14:17], v[6:9]
	s_waitcnt vmcnt(4)
	v_mfma_f32_16x16x32_bf16 v[2:5], v[2:5], v[18:21], v[6:9]
	s_waitcnt lgkmcnt(6)
	v_mfma_f32_16x16x32_bf16 v[42:45], v[10:13], v[14:17], v[6:9]
	v_mfma_f32_16x16x32_bf16 v[10:13], v[10:13], v[18:21], v[6:9]
	s_waitcnt lgkmcnt(5)
	v_mfma_f32_16x16x32_bf16 v[60:63], v[46:49], v[14:17], v[6:9]
	v_mfma_f32_16x16x32_bf16 v[46:49], v[46:49], v[18:21], v[6:9]
	s_waitcnt lgkmcnt(4)
	v_mfma_f32_16x16x32_bf16 v[64:67], v[56:59], v[14:17], v[6:9]
	v_mfma_f32_16x16x32_bf16 v[56:59], v[56:59], v[18:21], v[6:9]
	s_waitcnt lgkmcnt(3)
	v_mfma_f32_16x16x32_bf16 v[76:79], v[68:71], v[14:17], v[6:9]
	v_mfma_f32_16x16x32_bf16 v[68:71], v[68:71], v[18:21], v[6:9]
	s_waitcnt lgkmcnt(2)
	v_mfma_f32_16x16x32_bf16 v[80:83], v[72:75], v[14:17], v[6:9]
	v_mfma_f32_16x16x32_bf16 v[72:75], v[72:75], v[18:21], v[6:9]
	s_waitcnt lgkmcnt(1)
	v_mfma_f32_16x16x32_bf16 v[92:95], v[84:87], v[14:17], v[6:9]
	v_mfma_f32_16x16x32_bf16 v[84:87], v[84:87], v[18:21], v[6:9]
	s_waitcnt lgkmcnt(0)
	v_mfma_f32_16x16x32_bf16 v[96:99], v[88:91], v[14:17], v[6:9]
	v_mfma_f32_16x16x32_bf16 v[6:9], v[88:91], v[18:21], v[6:9]
	ds_read_b128 v[88:91], v121 offset:64
	ds_read_b128 v[100:103], v121 offset:3392
	s_waitcnt vmcnt(3) lgkmcnt(1)
	v_mfma_f32_16x16x32_bf16 v[38:41], v[88:91], v[22:25], v[38:41]
	s_waitcnt vmcnt(1)
	v_mfma_f32_16x16x32_bf16 v[2:5], v[88:91], v[30:33], v[2:5]
	s_waitcnt lgkmcnt(0)
; #define LASP __attribute__((address_space(3)))
; template <int DQK>
; __device__ __forceinline__ void flash_item(unsigned char* smem, const bf16_t* Q, int qs, const bf16_t* K0, const bf16_t* V0, int n0, const bf16_t* K1, const bf16_t* V1, int n1, int ks, int vs, bf16_t* Oo, int os, float shift) {
;     ...
;         for (int kk = 0; kk < NKK; ++kk) {
; #pragma unroll
;             for (int kg = 0; kg < NKG; ++kg) {
;                 const bf16x8_t kf = *(const LASP bf16x8_t*)(ls + (kg * 16 + fr) * KR + (kk * 32 + fq * 8) * 2);
;                 s[kg][0] = __builtin_amdgcn_mfma_f32_16x16x32_bf16(kf, qf[0][kk], s[kg][0], 0, 0, 0);
;                 s[kg][1] = __builtin_amdgcn_mfma_f32_16x16x32_bf16(kf, qf[1][kk], s[kg][1], 0, 0, 0);
;             }
;             asm volatile("" ::: "memory");
;         }
;         if (t + 1 < ntiles) FL_LOAD((t + 1) * KT);
; #pragma unroll
;         for (int qg = 0; qg < 2; ++qg) {
;             float ps = 0.f;
; #pragma unroll
;             for (int kg = 0; kg < NKG; ++kg)
; #pragma unroll
;                 for (int j = 0; j < 4; ++j) { const float p = __builtin_amdgcn_exp2f(s[kg][qg][j]); s[kg][qg][j] = p; ps += p; }
;             lsum[qg] += ps;
;         }
; #pragma unroll
;         for (int kp = 0; kp < NKP; ++kp) {
;             bf16x8_t pb[2];
; #pragma unroll
;             for (int qg = 0; qg < 2; ++qg) {
;                 const f32x4_t a = s[2 * kp][qg], b = s[2 * kp + 1][qg];
;                 u32x4_t pk; pk.x = pg8::cvt_pk_bf16(a[0], a[1]); pk.y = pg8::cvt_pk_bf16(a[2], a[3]); pk.z = pg8::cvt_pk_bf16(b[0], b[1]); pk.w = pg8::cvt_pk_bf16(b[2], b[3]);
;                 pb[qg] = __builtin_bit_cast(bf16x8_t, pk);
;             }
; #pragma unroll
;             for (int dg = 0; dg < 4; ++dg) {
;                 LASP unsigned char* va = ls + VOFF + (32 * kp + 4 * fq + (fr >> 2)) * VR + (16 * dg + 4 * (fr & 3)) * 2;
;                 const s16x4 v0 = __builtin_amdgcn_ds_read_tr16_b64_v4i16((LASP s16x4*)va);
;                 const s16x4 v1 = __builtin_amdgcn_ds_read_tr16_b64_v4i16((LASP s16x4*)(va + 16 * VR));
;                 const bf16x8_t vf = __builtin_shufflevector(v0, v1, 0, 1, 2, 3, 4, 5, 6, 7);
;                 o[dg][0] = __builtin_amdgcn_mfma_f32_16x16x32_bf16(vf, pb[0], o[dg][0], 0, 0, 0);
;                 o[dg][1] = __builtin_amdgcn_mfma_f32_16x16x32_bf16(vf, pb[1], o[dg][1], 0, 0, 0);
;             }
	v_mfma_f32_16x16x32_bf16 v[42:45], v[100:103], v[22:25], v[42:45]
	v_mfma_f32_16x16x32_bf16 v[10:13], v[100:103], v[30:33], v[10:13]
	ds_read_b128 v[88:91], v121 offset:6720
	ds_read_b128 v[100:103], v121 offset:10048
	s_waitcnt lgkmcnt(1)
	v_mfma_f32_16x16x32_bf16 v[60:63], v[88:91], v[22:25], v[60:63]
	v_mfma_f32_16x16x32_bf16 v[46:49], v[88:91], v[30:33], v[46:49]
	s_waitcnt lgkmcnt(0)
	v_mfma_f32_16x16x32_bf16 v[64:67], v[100:103], v[22:25], v[64:67]
	v_mfma_f32_16x16x32_bf16 v[56:59], v[100:103], v[30:33], v[56:59]
	ds_read_b128 v[88:91], v121 offset:13376
	ds_read_b128 v[100:103], v121 offset:16704
	s_waitcnt lgkmcnt(1)
	v_mfma_f32_16x16x32_bf16 v[76:79], v[88:91], v[22:25], v[76:79]
	v_mfma_f32_16x16x32_bf16 v[68:71], v[88:91], v[30:33], v[68:71]
	s_waitcnt lgkmcnt(0)
	v_mfma_f32_16x16x32_bf16 v[80:83], v[100:103], v[22:25], v[80:83]
	v_mfma_f32_16x16x32_bf16 v[72:75], v[100:103], v[30:33], v[72:75]
	ds_read_b128 v[88:91], v121 offset:20032
	ds_read_b128 v[100:103], v121 offset:23360
	s_waitcnt lgkmcnt(1)
	v_mfma_f32_16x16x32_bf16 v[92:95], v[88:91], v[22:25], v[92:95]
	v_mfma_f32_16x16x32_bf16 v[84:87], v[88:91], v[30:33], v[84:87]
	s_waitcnt lgkmcnt(0)
	v_mfma_f32_16x16x32_bf16 v[88:91], v[100:103], v[22:25], v[96:99]
	v_mfma_f32_16x16x32_bf16 v[96:99], v[100:103], v[30:33], v[6:9]
	s_nop 2
	ds_read_b128 v[6:9], v121 offset:128
	ds_read_b128 v[100:103], v121 offset:3456
	s_waitcnt vmcnt(0) lgkmcnt(1)
	v_mfma_f32_16x16x32_bf16 v[104:107], v[6:9], v[34:37], v[38:41]
	v_mfma_f32_16x16x32_bf16 v[108:111], v[6:9], v[26:29], v[2:5]
	s_nop 2
	ds_read_b128 v[2:5], v121 offset:6784
	ds_read_b128 v[6:9], v121 offset:10112
	s_waitcnt lgkmcnt(1)
	v_mfma_f32_16x16x32_bf16 v[60:63], v[2:5], v[34:37], v[60:63]
	v_mfma_f32_16x16x32_bf16 v[116:119], v[2:5], v[26:29], v[46:49]
	s_waitcnt lgkmcnt(0)
	v_mfma_f32_16x16x32_bf16 v[64:67], v[6:9], v[34:37], v[64:67]
	v_mfma_f32_16x16x32_bf16 v[56:59], v[6:9], v[26:29], v[56:59]
	ds_read_b128 v[2:5], v121 offset:13440
	ds_read_b128 v[6:9], v121 offset:16768
	v_mfma_f32_16x16x32_bf16 v[112:115], v[100:103], v[34:37], v[42:45]
	s_waitcnt lgkmcnt(1)
	v_mfma_f32_16x16x32_bf16 v[132:135], v[2:5], v[34:37], v[76:79]
	v_mfma_f32_16x16x32_bf16 v[46:49], v[2:5], v[26:29], v[68:71]
	s_nop 4
	v_exp_f32_e32 v79, v115
	s_nop 0
	v_exp_f32_e32 v125, v132
	v_lshl_add_u64 v[76:77], v[52:53], 0, s[14:15]
	s_waitcnt lgkmcnt(0)
	v_mfma_f32_16x16x32_bf16 v[42:45], v[6:9], v[26:29], v[72:75]
	ds_read_b128 v[2:5], v121 offset:20096
	s_nop 1
	ds_read_b128 v[72:75], v121 offset:23424
	v_exp_f32_e32 v124, v46
	v_mfma_f32_16x16x32_bf16 v[100:103], v[100:103], v[26:29], v[10:13]
	v_mfma_f32_16x16x32_bf16 v[68:71], v[6:9], v[34:37], v[80:83]
	s_waitcnt lgkmcnt(1)
	v_mfma_f32_16x16x32_bf16 v[38:41], v[2:5], v[34:37], v[92:95]
	s_nop 0
	v_exp_f32_e32 v83, v113
	v_exp_f32_e32 v81, v114
	s_nop 1
	v_exp_f32_e32 v82, v101
	v_mfma_f32_16x16x32_bf16 v[6:9], v[2:5], v[26:29], v[84:87]
	v_bfe_u32 v2, v126, 2, 2
	v_or_b32_e32 v194, v145, v2
	v_mad_u32_u24 v55, v194, s89, v131
	s_waitcnt lgkmcnt(0)
	v_mfma_f32_16x16x32_bf16 v[10:13], v[72:75], v[34:37], v[88:91]
	v_exp_f32_e32 v93, v104
	v_exp_f32_e32 v87, v107
	v_exp_f32_e32 v85, v112
	v_mfma_f32_16x16x32_bf16 v[2:5], v[72:75], v[26:29], v[96:99]
	v_exp_f32_e32 v91, v105
	v_exp_f32_e32 v89, v106
	v_exp_f32_e32 v92, v108
	v_exp_f32_e32 v90, v109
	v_exp_f32_e32 v88, v110
	v_exp_f32_e32 v86, v111
	v_exp_f32_e32 v84, v100
	v_exp_f32_e32 v80, v102
	v_exp_f32_e32 v78, v103
	ds_read_b64_tr_b16 v[96:97], v55 offset:35072
	ds_read_b64_tr_b16 v[94:95], v55 offset:32768
	ds_read_b64_tr_b16 v[98:99], v55 offset:32800
	ds_read_b64_tr_b16 v[120:121], v55 offset:32832
	ds_read_b64_tr_b16 v[136:137], v55 offset:32864
	ds_read_b64_tr_b16 v[100:101], v55 offset:35104
	ds_read_b64_tr_b16 v[122:123], v55 offset:35136
	ds_read_b64_tr_b16 v[138:139], v55 offset:35168
	v_cvt_pk_bf16_f32 v72, v93, v91
	v_cvt_pk_bf16_f32 v73, v89, v87
	v_cvt_pk_bf16_f32 v74, v85, v83
	v_cvt_pk_bf16_f32 v75, v81, v79
	v_cvt_pk_bf16_f32 v110, v92, v90
	v_cvt_pk_bf16_f32 v111, v88, v86
	v_cvt_pk_bf16_f32 v112, v84, v82
	v_cvt_pk_bf16_f32 v113, v80, v78
	s_waitcnt lgkmcnt(6)
	v_mfma_f32_16x16x32_bf16 v[146:149], v[94:97], v[72:75], 0
	v_exp_f32_e32 v109, v60
	v_exp_f32_e32 v107, v61
	v_exp_f32_e32 v105, v62
	v_mfma_f32_16x16x32_bf16 v[150:153], v[94:97], v[110:113], 0
	v_exp_f32_e32 v103, v63
	v_exp_f32_e32 v97, v66
	v_exp_f32_e32 v95, v67
	s_waitcnt lgkmcnt(2)
	v_mfma_f32_16x16x32_bf16 v[156:159], v[98:101], v[72:75], 0
	v_exp_f32_e32 v108, v116
	v_exp_f32_e32 v106, v117
	v_exp_f32_e32 v104, v118
	v_mfma_f32_16x16x32_bf16 v[60:63], v[98:101], v[110:113], 0
	v_exp_f32_e32 v101, v64
	v_exp_f32_e32 v99, v65
	v_exp_f32_e32 v102, v119
	s_waitcnt lgkmcnt(1)
	v_mfma_f32_16x16x32_bf16 v[64:67], v[120:123], v[110:113], 0
	v_exp_f32_e32 v100, v56
	v_exp_f32_e32 v98, v57
	v_exp_f32_e32 v96, v58
	v_exp_f32_e32 v94, v59
	s_waitcnt lgkmcnt(0)
	v_mfma_f32_16x16x32_bf16 v[56:59], v[136:139], v[110:113], 0
	ds_read_b64_tr_b16 v[110:111], v55 offset:37376
	ds_read_b64_tr_b16 v[112:113], v55 offset:39680
	ds_read_b64_tr_b16 v[114:115], v55 offset:37408
	ds_read_b64_tr_b16 v[168:169], v55 offset:37440
	ds_read_b64_tr_b16 v[172:173], v55 offset:37472
	ds_read_b64_tr_b16 v[116:117], v55 offset:39712
	ds_read_b64_tr_b16 v[170:171], v55 offset:39744
	ds_read_b64_tr_b16 v[174:175], v55 offset:39776
	v_cvt_pk_bf16_f32 v164, v108, v106
	v_mfma_f32_16x16x32_bf16 v[160:163], v[120:123], v[72:75], 0
	v_cvt_pk_bf16_f32 v165, v104, v102
	v_cvt_pk_bf16_f32 v166, v100, v98
	v_cvt_pk_bf16_f32 v167, v96, v94
	v_mfma_f32_16x16x32_bf16 v[72:75], v[136:139], v[72:75], 0
	v_cvt_pk_bf16_f32 v136, v109, v107
	v_cvt_pk_bf16_f32 v137, v105, v103
	v_cvt_pk_bf16_f32 v138, v101, v99
	v_cvt_pk_bf16_f32 v139, v97, v95
	s_waitcnt lgkmcnt(6)
; __device__ __forceinline__ unsigned cvt_pk_bf16(float lo, float hi) { const f32x2c f = {lo, hi}; return __builtin_bit_cast(unsigned, __builtin_convertvector(f, bf16x2c)); }
; #define LASP __attribute__((address_space(3)))
; template <int DQK>
; __device__ __forceinline__ void flash_item(unsigned char* smem, const bf16_t* Q, int qs, const bf16_t* K0, const bf16_t* V0, int n0, const bf16_t* K1, const bf16_t* V1, int n1, int ks, int vs, bf16_t* Oo, int os, float shift) {
;     ...
;         for (int qg = 0; qg < 2; ++qg) {
;             float ps = 0.f;
; #pragma unroll
;             for (int kg = 0; kg < NKG; ++kg)
; #pragma unroll
;                 for (int j = 0; j < 4; ++j) { const float p = __builtin_amdgcn_exp2f(s[kg][qg][j]); s[kg][qg][j] = p; ps += p; }
;             lsum[qg] += ps;
;         }
; #pragma unroll
;         for (int kp = 0; kp < NKP; ++kp) {
;             bf16x8_t pb[2];
; #pragma unroll
;             for (int qg = 0; qg < 2; ++qg) {
;                 const f32x4_t a = s[2 * kp][qg], b = s[2 * kp + 1][qg];
;                 u32x4_t pk; pk.x = pg8::cvt_pk_bf16(a[0], a[1]); pk.y = pg8::cvt_pk_bf16(a[2], a[3]); pk.z = pg8::cvt_pk_bf16(b[0], b[1]); pk.w = pg8::cvt_pk_bf16(b[2], b[3]);
;                 pb[qg] = __builtin_bit_cast(bf16x8_t, pk);
;             }
; #pragma unroll
;             for (int dg = 0; dg < 4; ++dg) {
;                 LASP unsigned char* va = ls + VOFF + (32 * kp + 4 * fq + (fr >> 2)) * VR + (16 * dg + 4 * (fr & 3)) * 2;
;                 const s16x4 v0 = __builtin_amdgcn_ds_read_tr16_b64_v4i16((LASP s16x4*)va);
;                 const s16x4 v1 = __builtin_amdgcn_ds_read_tr16_b64_v4i16((LASP s16x4*)(va + 16 * VR));
;                 const bf16x8_t vf = __builtin_shufflevector(v0, v1, 0, 1, 2, 3, 4, 5, 6, 7);
;                 o[dg][0] = __builtin_amdgcn_mfma_f32_16x16x32_bf16(vf, pb[0], o[dg][0], 0, 0, 0);
;                 o[dg][1] = __builtin_amdgcn_mfma_f32_16x16x32_bf16(vf, pb[1], o[dg][1], 0, 0, 0);
;             }
	v_mfma_f32_16x16x32_bf16 v[150:153], v[110:113], v[164:167], v[150:153]
	v_exp_f32_e32 v123, v133
	v_exp_f32_e32 v121, v134
	v_exp_f32_e32 v119, v135
	v_mfma_f32_16x16x32_bf16 v[146:149], v[110:113], v[136:139], v[146:149]
	v_exp_f32_e32 v113, v70
	v_exp_f32_e32 v111, v71
	v_exp_f32_e32 v122, v47
	s_waitcnt lgkmcnt(2)
	v_mfma_f32_16x16x32_bf16 v[156:159], v[114:117], v[136:139], v[156:159]
	v_exp_f32_e32 v120, v48
	v_exp_f32_e32 v118, v49
	v_exp_f32_e32 v112, v44
	v_mfma_f32_16x16x32_bf16 v[60:63], v[114:117], v[164:167], v[60:63]
	v_exp_f32_e32 v117, v68
	v_exp_f32_e32 v115, v69
	v_exp_f32_e32 v116, v42
	v_exp_f32_e32 v114, v43
	v_exp_f32_e32 v110, v45
	ds_read_b64_tr_b16 v[68:69], v55 offset:41984
	ds_read_b64_tr_b16 v[70:71], v55 offset:44288
	s_waitcnt lgkmcnt(3)
	v_mfma_f32_16x16x32_bf16 v[132:135], v[168:171], v[136:139], v[160:163]
	v_exp_f32_e32 v141, v38
	v_exp_f32_e32 v181, v39
	v_exp_f32_e32 v183, v40
	v_mfma_f32_16x16x32_bf16 v[64:67], v[168:171], v[164:167], v[64:67]
	v_exp_f32_e32 v185, v41
	v_exp_f32_e32 v187, v10
	v_exp_f32_e32 v189, v11
	s_waitcnt lgkmcnt(2)
	v_mfma_f32_16x16x32_bf16 v[46:49], v[172:175], v[136:139], v[72:75]
	v_exp_f32_e32 v191, v12
	v_exp_f32_e32 v193, v13
	v_exp_f32_e32 v140, v6
	v_mfma_f32_16x16x32_bf16 v[42:45], v[172:175], v[164:167], v[56:59]
	ds_read_b64_tr_b16 v[136:137], v55 offset:42016
	ds_read_b64_tr_b16 v[160:161], v55 offset:42048
	ds_read_b64_tr_b16 v[164:165], v55 offset:42080
	ds_read_b64_tr_b16 v[138:139], v55 offset:44320
	ds_read_b64_tr_b16 v[162:163], v55 offset:44352
	ds_read_b64_tr_b16 v[166:167], v55 offset:44384
	v_cvt_pk_bf16_f32 v56, v125, v123
	v_cvt_pk_bf16_f32 v57, v121, v119
	v_cvt_pk_bf16_f32 v58, v117, v115
	v_cvt_pk_bf16_f32 v59, v113, v111
	v_cvt_pk_bf16_f32 v72, v124, v122
	v_cvt_pk_bf16_f32 v73, v120, v118
	v_cvt_pk_bf16_f32 v74, v116, v114
	v_cvt_pk_bf16_f32 v75, v112, v110
	v_exp_f32_e32 v180, v7
	v_exp_f32_e32 v182, v8
	v_exp_f32_e32 v184, v9
	v_exp_f32_e32 v186, v2
	v_exp_f32_e32 v188, v3
	v_exp_f32_e32 v190, v4
	v_exp_f32_e32 v192, v5
	ds_read_b64_tr_b16 v[2:3], v55 offset:46592
	ds_read_b64_tr_b16 v[4:5], v55 offset:48896
	s_waitcnt lgkmcnt(8)
	v_mfma_f32_16x16x32_bf16 v[146:149], v[68:71], v[56:59], v[146:149]
	ds_read_b64_tr_b16 v[6:7], v55 offset:46624
	ds_read_b64_tr_b16 v[172:173], v55 offset:46656
	ds_read_b64_tr_b16 v[176:177], v55 offset:46688
	ds_read_b64_tr_b16 v[8:9], v55 offset:48928
	ds_read_b64_tr_b16 v[174:175], v55 offset:48960
	ds_read_b64_tr_b16 v[178:179], v55 offset:48992
	v_cvt_pk_bf16_f32 v168, v140, v180
	v_cvt_pk_bf16_f32 v169, v182, v184
	v_mfma_f32_16x16x32_bf16 v[68:71], v[68:71], v[72:75], v[150:153]
	v_cvt_pk_bf16_f32 v170, v186, v188
	v_cvt_pk_bf16_f32 v171, v190, v192
	v_add_f32_e32 v92, 0, v92
	v_add_f32_e32 v93, 0, v93
	s_waitcnt lgkmcnt(10)
	v_mfma_f32_16x16x32_bf16 v[150:153], v[136:139], v[56:59], v[156:159]
	v_add_f32_e64 v90, v90, v92
	v_add_f32_e64 v91, v91, v93
	v_add_f32_e32 v88, v88, v90
	v_add_f32_e32 v89, v89, v91
	v_mfma_f32_16x16x32_bf16 v[136:139], v[136:139], v[72:75], v[60:63]
	v_add_f32_e64 v86, v86, v88
	v_add_f32_e64 v87, v87, v89
	v_add_f32_e32 v84, v84, v86
	v_add_f32_e32 v85, v85, v87
	s_waitcnt lgkmcnt(9)
	v_mfma_f32_16x16x32_bf16 v[132:135], v[160:163], v[56:59], v[132:135]
	v_add_f32_e64 v82, v82, v84
	v_add_f32_e64 v83, v83, v85
	v_add_f32_e32 v80, v80, v82
	v_add_f32_e32 v81, v81, v83
	v_mfma_f32_16x16x32_bf16 v[10:13], v[160:163], v[72:75], v[64:67]
	v_add_f32_e64 v78, v78, v80
	v_add_f32_e64 v79, v79, v81
	v_and_b32_e32 v80, 7, v126
	v_add_f32_e32 v78, v108, v78
	v_add_f32_e32 v79, v109, v79
	s_waitcnt lgkmcnt(8)
	v_mfma_f32_16x16x32_bf16 v[156:159], v[164:167], v[56:59], v[46:49]
	v_lshl_add_u64 v[56:57], v[50:51], 0, s[36:37]
	global_load_dwordx4 v[38:41], v[76:77], off offset:64
	s_nop 0
	global_load_dwordx4 v[46:49], v[76:77], off offset:128
	v_mad_i64_i32 v[50:51], s[18:19], v129, s87, v[56:57]
	v_mfma_f32_16x16x32_bf16 v[160:163], v[164:167], v[72:75], v[42:45]
	v_cvt_pk_bf16_f32 v164, v141, v181
	v_cvt_pk_bf16_f32 v165, v183, v185
	v_cvt_pk_bf16_f32 v166, v187, v189
	v_cvt_pk_bf16_f32 v167, v191, v193
	v_add_co_u32_e32 v42, vcc, s5, v52
	s_waitcnt lgkmcnt(6)
	v_mfma_f32_16x16x32_bf16 v[62:65], v[2:5], v[164:167], v[146:149]
	v_addc_co_u32_e32 v43, vcc, 0, v53, vcc
	global_load_dwordx4 v[42:45], v[42:43], off
	s_nop 0
	global_load_dwordx4 v[50:53], v[50:51], off
	v_mfma_f32_16x16x32_bf16 v[58:61], v[2:5], v[168:171], v[68:71]
	v_add_f32_e64 v78, v106, v78
	v_add_f32_e64 v79, v107, v79
	s_mul_hi_i32 s5, s2, 0x240000
	v_add_f32_e32 v78, v104, v78
	v_add_f32_e32 v79, v105, v79
	s_waitcnt lgkmcnt(2)
	v_mfma_f32_16x16x32_bf16 v[74:77], v[6:9], v[164:167], v[150:153]
	v_add_f32_e64 v78, v102, v78
	v_add_f32_e64 v79, v103, v79
	v_add_f32_e32 v78, v100, v78
	v_add_f32_e32 v79, v101, v79
	v_mfma_f32_16x16x32_bf16 v[2:5], v[6:9], v[168:171], v[136:139]
	v_mad_i64_i32 v[6:7], s[18:19], v54, s87, v[56:57]
	global_load_dwordx4 v[54:57], v[6:7], off
	v_add_f32_e32 v78, v98, v78
	v_add_f32_e32 v79, v99, v79
	s_waitcnt lgkmcnt(1)
	v_mfma_f32_16x16x32_bf16 v[70:73], v[172:175], v[164:167], v[132:135]
	v_add_f32_e64 v78, v96, v78
	v_add_f32_e64 v79, v97, v79
	v_add_f32_e32 v78, v94, v78
	v_add_f32_e32 v79, v95, v79
	s_waitcnt lgkmcnt(0)
; __device__ __forceinline__ unsigned cvt_pk_bf16(float lo, float hi) { const f32x2c f = {lo, hi}; return __builtin_bit_cast(unsigned, __builtin_convertvector(f, bf16x2c)); }
; #define LASP __attribute__((address_space(3)))
; template <int DQK>
; __device__ __forceinline__ void flash_item(unsigned char* smem, const bf16_t* Q, int qs, const bf16_t* K0, const bf16_t* V0, int n0, const bf16_t* K1, const bf16_t* V1, int n1, int ks, int vs, bf16_t* Oo, int os, float shift) {
;     ...
;         for (int qg = 0; qg < 2; ++qg) {
;             float ps = 0.f;
; #pragma unroll
;             for (int kg = 0; kg < NKG; ++kg)
; #pragma unroll
;                 for (int j = 0; j < 4; ++j) { const float p = __builtin_amdgcn_exp2f(s[kg][qg][j]); s[kg][qg][j] = p; ps += p; }
;             lsum[qg] += ps;
;         }
; #pragma unroll
;         for (int kp = 0; kp < NKP; ++kp) {
;             bf16x8_t pb[2];
; #pragma unroll
;             for (int qg = 0; qg < 2; ++qg) {
;                 const f32x4_t a = s[2 * kp][qg], b = s[2 * kp + 1][qg];
;                 u32x4_t pk; pk.x = pg8::cvt_pk_bf16(a[0], a[1]); pk.y = pg8::cvt_pk_bf16(a[2], a[3]); pk.z = pg8::cvt_pk_bf16(b[0], b[1]); pk.w = pg8::cvt_pk_bf16(b[2], b[3]);
;                 pb[qg] = __builtin_bit_cast(bf16x8_t, pk);
;             }
; #pragma unroll
;             for (int dg = 0; dg < 4; ++dg) {
;                 LASP unsigned char* va = ls + VOFF + (32 * kp + 4 * fq + (fr >> 2)) * VR + (16 * dg + 4 * (fr & 3)) * 2;
;                 const s16x4 v0 = __builtin_amdgcn_ds_read_tr16_b64_v4i16((LASP s16x4*)va);
;                 const s16x4 v1 = __builtin_amdgcn_ds_read_tr16_b64_v4i16((LASP s16x4*)(va + 16 * VR));
;                 const bf16x8_t vf = __builtin_shufflevector(v0, v1, 0, 1, 2, 3, 4, 5, 6, 7);
;                 o[dg][0] = __builtin_amdgcn_mfma_f32_16x16x32_bf16(vf, pb[0], o[dg][0], 0, 0, 0);
;                 o[dg][1] = __builtin_amdgcn_mfma_f32_16x16x32_bf16(vf, pb[1], o[dg][1], 0, 0, 0);
;             }
	v_mfma_f32_16x16x32_bf16 v[66:69], v[176:179], v[164:167], v[156:159]
	v_add_f32_e64 v78, v124, v78
	v_add_f32_e64 v79, v125, v79
	v_mad_i64_i32 v[132:133], s[18:19], v129, s87, 0
	v_add_f32_e32 v78, v122, v78
	v_add_f32_e32 v79, v123, v79
	v_mfma_f32_16x16x32_bf16 v[6:9], v[172:175], v[168:171], v[10:13]
	v_add_f32_e64 v78, v120, v78
	v_add_f32_e64 v79, v121, v79
	v_mul_u32_u24_e32 v129, 0xd0, v130
	v_add_f32_e32 v78, v118, v78
	v_add_f32_e32 v79, v119, v79
	v_mfma_f32_16x16x32_bf16 v[10:13], v[176:179], v[168:171], v[160:163]
	v_add_f32_e64 v78, v116, v78
	v_add_f32_e64 v79, v117, v79
	v_mul_u32_u24_e32 v130, 0x90, v194
	v_add_f32_e32 v78, v114, v78
	v_add_f32_e32 v79, v115, v79
	v_add_u32_e32 v162, v128, v129
	v_add_f32_e32 v78, v112, v78
	v_add_f32_e32 v79, v113, v79
	v_add_u32_e32 v163, v131, v130
	v_add_f32_e32 v78, v110, v78
	v_add_f32_e32 v79, v111, v79
	v_add_f32_e32 v78, v140, v78
	v_add_f32_e32 v79, v141, v79
	v_add_f32_e32 v78, v180, v78
	v_add_f32_e32 v79, v181, v79
	v_add_f32_e32 v78, v182, v78
	v_add_f32_e32 v79, v183, v79
	v_add_f32_e32 v78, v184, v78
	v_add_f32_e32 v79, v185, v79
	v_add_f32_e32 v78, v186, v78
	v_add_f32_e32 v79, v187, v79
	v_add_f32_e32 v78, v188, v78
	v_add_f32_e32 v79, v189, v79
	v_add_f32_e32 v78, v190, v78
	v_add_f32_e32 v79, v191, v79
	v_add_f32_e32 v78, v192, v78
	v_add_f32_e32 v79, v193, v79
	v_add_f32_e32 v156, 0, v78
	v_add_f32_e32 v157, 0, v79
	v_mov_b32_e32 v78, 0x180000
	v_mad_i64_i32 v[78:79], s[18:19], s2, v78, v[132:133]
	s_add_u32 s18, s38, 0x19418040
	v_lshl_or_b32 v78, v80, 4, v78
	s_addc_u32 s19, s5, 0
	v_lshl_add_u64 v[158:159], v[78:79], 0, s[20:21]
	v_mov_b64_e32 v[78:79], s[18:19]
	v_mad_i64_i32 v[78:79], s[18:19], v127, s91, v[78:79]
	v_and_b32_e32 v80, 3, v126
	v_lshl_or_b32 v78, v80, 4, v78
	v_lshl_add_u64 v[160:161], v[78:79], 0, s[16:17]
	v_xor_b32_e32 v1, 0x10000, v1
	v_xor_b32_e32 v143, 0x10000, v143
	s_waitcnt vmcnt(2)
	ds_write_b128 v1, v[42:45]
	ds_write_b128 v1, v[38:41] offset:64
	ds_write_b128 v1, v[46:49] offset:128
	s_waitcnt vmcnt(1)
	ds_write_b128 v143, v[50:53] offset:32768
	s_waitcnt vmcnt(0)
	ds_write_b128 v143, v[54:57] offset:41984
	v_xor_b32_e32 v162, 0x10000, v162
	v_xor_b32_e32 v163, 0x10000, v163
	s_waitcnt lgkmcnt(0)
	s_barrier
	s_branch .LBB0_832
.LBB0_831:
	ds_read_b64_tr_b16 v[182:183], v163 offset:35072
	ds_read_b64_tr_b16 v[180:181], v163 offset:32768
	ds_read_b64_tr_b16 v[184:185], v163 offset:32832
	ds_read_b64_tr_b16 v[186:187], v163 offset:35136
	ds_read_b64_tr_b16 v[188:189], v163 offset:32864
	ds_read_b64_tr_b16 v[190:191], v163 offset:35168
	ds_read_b64_tr_b16 v[192:193], v163 offset:32800
	ds_read_b64_tr_b16 v[194:195], v163 offset:35104
	ds_read_b64_tr_b16 v[196:197], v163 offset:37376
	ds_read_b64_tr_b16 v[198:199], v163 offset:39680
	ds_read_b64_tr_b16 v[200:201], v163 offset:37408
	ds_read_b64_tr_b16 v[202:203], v163 offset:39712
	s_nop 0
	v_exp_f32_e32 v148, v138
	v_exp_f32_e32 v149, v139
	v_exp_f32_e32 v150, v140
	v_exp_f32_e32 v151, v141
	v_add_f32_e32 v138, 0, v148
	v_exp_f32_e32 v152, v134
	v_add_f32_e32 v138, v149, v138
	v_exp_f32_e32 v153, v135
	v_add_f32_e32 v138, v150, v138
	v_exp_f32_e32 v166, v136
	v_add_f32_e32 v138, v151, v138
	v_exp_f32_e32 v167, v137
	v_add_f32_e32 v134, v152, v138
	v_exp_f32_e32 v136, v130
	v_add_f32_e32 v134, v153, v134
	v_exp_f32_e32 v137, v131
	v_add_f32_e32 v134, v166, v134
	v_exp_f32_e32 v138, v132
	v_add_f32_e32 v134, v167, v134
	v_exp_f32_e32 v139, v133
	v_add_f32_e32 v130, v136, v134
	v_exp_f32_e32 v140, v126
	v_add_f32_e32 v130, v137, v130
	v_exp_f32_e32 v141, v127
	v_add_f32_e32 v130, v138, v130
	v_exp_f32_e32 v164, v128
	v_add_f32_e32 v130, v139, v130
	v_exp_f32_e32 v165, v129
	v_add_f32_e32 v126, v140, v130
	v_exp_f32_e32 v130, v110
	v_add_f32_e32 v126, v141, v126
	v_exp_f32_e32 v131, v111
	v_add_f32_e32 v126, v164, v126
	v_exp_f32_e32 v132, v112
	v_add_f32_e32 v126, v165, v126
	v_exp_f32_e32 v133, v113
	v_add_f32_e32 v110, v130, v126
	v_exp_f32_e32 v134, v118
	v_add_f32_e32 v110, v131, v110
	v_exp_f32_e32 v135, v119
	v_exp_f32_e32 v102, v102
	v_add_f32_e32 v110, v132, v110
	v_exp_f32_e32 v103, v103
	v_add_f32_e32 v110, v133, v110
	v_exp_f32_e32 v104, v104
	v_add_f32_e32 v110, v134, v110
	v_exp_f32_e32 v105, v105
	v_add_f32_e32 v147, v135, v110
	v_add_f32_e32 v110, 0, v102
	v_exp_f32_e32 v168, v86
	v_add_f32_e32 v110, v103, v110
	v_exp_f32_e32 v169, v87
	v_add_f32_e32 v110, v104, v110
	v_exp_f32_e32 v170, v88
	v_add_f32_e32 v110, v105, v110
	v_exp_f32_e32 v171, v89
	v_add_f32_e32 v86, v168, v110
	v_exp_f32_e32 v172, v78
	v_add_f32_e32 v86, v169, v86
	v_exp_f32_e32 v173, v79
	v_add_f32_e32 v86, v170, v86
	v_exp_f32_e32 v174, v80
	v_add_f32_e32 v86, v171, v86
	v_exp_f32_e32 v175, v81
	v_add_f32_e32 v78, v172, v86
	v_exp_f32_e32 v176, v90
	v_add_f32_e32 v78, v173, v78
	v_exp_f32_e32 v177, v91
	v_add_f32_e32 v78, v174, v78
	v_exp_f32_e32 v178, v92
	v_add_f32_e32 v78, v175, v78
	v_exp_f32_e32 v179, v93
	v_add_f32_e32 v78, v176, v78
	v_exp_f32_e32 v86, v82
	v_add_f32_e32 v78, v177, v78
	v_exp_f32_e32 v87, v83
	v_add_f32_e32 v78, v178, v78
	v_exp_f32_e32 v88, v84
	v_add_f32_e32 v78, v179, v78
	v_exp_f32_e32 v89, v85
	v_add_f32_e32 v78, v86, v78
	v_exp_f32_e32 v90, v98
	v_add_f32_e32 v78, v87, v78
	v_exp_f32_e32 v91, v99
	v_exp_f32_e32 v127, v120
	v_add_f32_e32 v78, v88, v78
	v_exp_f32_e32 v126, v100
	v_exp_f32_e32 v129, v121
	v_add_f32_e32 v78, v89, v78
	v_exp_f32_e32 v128, v101
	v_exp_f32_e32 v111, v114
	v_add_f32_e32 v78, v90, v78
	v_exp_f32_e32 v110, v94
	v_exp_f32_e32 v115, v115
	v_add_f32_e32 v146, v91, v78
	v_exp_f32_e32 v114, v95
	v_exp_f32_e32 v113, v116
	v_exp_f32_e32 v112, v96
	v_add_f32_e32 v78, v126, v146
	v_add_f32_e32 v79, v127, v147
	v_exp_f32_e32 v119, v117
	v_exp_f32_e32 v118, v97
	v_add_f32_e32 v78, v128, v78
	v_add_f32_e32 v79, v129, v79
	v_exp_f32_e32 v117, v122
	v_exp_f32_e32 v116, v106
	v_add_f32_e32 v78, v110, v78
	v_add_f32_e32 v79, v111, v79
	v_exp_f32_e32 v123, v123
	v_exp_f32_e32 v122, v107
	v_add_f32_e32 v78, v114, v78
	v_add_f32_e32 v79, v115, v79
	v_exp_f32_e32 v121, v124
	v_exp_f32_e32 v120, v108
	v_add_f32_e32 v78, v112, v78
	v_add_f32_e32 v79, v113, v79
	v_exp_f32_e32 v125, v125
	v_exp_f32_e32 v124, v109
	v_add_f32_e32 v78, v118, v78
	v_add_f32_e32 v79, v119, v79
	v_add_f32_e32 v78, v116, v78
	v_add_f32_e32 v79, v117, v79
	v_cvt_pk_bf16_f32 v82, v148, v149
	v_add_f32_e32 v78, v122, v78
	v_add_f32_e32 v79, v123, v79
	v_cvt_pk_bf16_f32 v83, v150, v151
	v_add_f32_e32 v78, v120, v78
	v_add_f32_e32 v79, v121, v79
	v_cvt_pk_bf16_f32 v84, v152, v153
	v_add_f32_e32 v78, v124, v78
	v_add_f32_e32 v79, v125, v79
	v_cvt_pk_bf16_f32 v85, v166, v167
	v_add_f32_e32 v156, v156, v78
	v_add_f32_e32 v157, v157, v79
	v_cvt_pk_bf16_f32 v78, v102, v103
	v_cvt_pk_bf16_f32 v79, v104, v105
	v_cvt_pk_bf16_f32 v80, v168, v169
	v_cvt_pk_bf16_f32 v81, v170, v171
	ds_read_b64_tr_b16 v[204:205], v163 offset:37440
	ds_read_b64_tr_b16 v[206:207], v163 offset:39744
	s_waitcnt lgkmcnt(12)
; __device__ __forceinline__ unsigned cvt_pk_bf16(float lo, float hi) { const f32x2c f = {lo, hi}; return __builtin_bit_cast(unsigned, __builtin_convertvector(f, bf16x2c)); }
; #define LASP __attribute__((address_space(3)))
; template <int DQK>
; __device__ __forceinline__ void flash_item(unsigned char* smem, const bf16_t* Q, int qs, const bf16_t* K0, const bf16_t* V0, int n0, const bf16_t* K1, const bf16_t* V1, int n1, int ks, int vs, bf16_t* Oo, int os, float shift) {
;     ...
;         for (int c = 0; c < NKC; ++c) *(LASP u32x4_t*)(ls + (tid >> 2) * KR + ((tid & 3) + 4 * c) * 16) = kreg[c];
; #pragma unroll
;         for (int c = 0; c < NVC; ++c) *(LASP u32x4_t*)(ls + VOFF + ((tid >> 3) + 64 * c) * VR + (tid & 7) * 16) = vreg[c];
;         __syncthreads();
;     ...
;         for (int kp = 0; kp < NKP; ++kp) {
;             bf16x8_t pb[2];
; #pragma unroll
;             for (int qg = 0; qg < 2; ++qg) {
;                 const f32x4_t a = s[2 * kp][qg], b = s[2 * kp + 1][qg];
;                 u32x4_t pk; pk.x = pg8::cvt_pk_bf16(a[0], a[1]); pk.y = pg8::cvt_pk_bf16(a[2], a[3]); pk.z = pg8::cvt_pk_bf16(b[0], b[1]); pk.w = pg8::cvt_pk_bf16(b[2], b[3]);
;                 pb[qg] = __builtin_bit_cast(bf16x8_t, pk);
;             }
; #pragma unroll
;             for (int dg = 0; dg < 4; ++dg) {
;                 LASP unsigned char* va = ls + VOFF + (32 * kp + 4 * fq + (fr >> 2)) * VR + (16 * dg + 4 * (fr & 3)) * 2;
;                 const s16x4 v0 = __builtin_amdgcn_ds_read_tr16_b64_v4i16((LASP s16x4*)va);
;                 const s16x4 v1 = __builtin_amdgcn_ds_read_tr16_b64_v4i16((LASP s16x4*)(va + 16 * VR));
;                 const bf16x8_t vf = __builtin_shufflevector(v0, v1, 0, 1, 2, 3, 4, 5, 6, 7);
;                 o[dg][0] = __builtin_amdgcn_mfma_f32_16x16x32_bf16(vf, pb[0], o[dg][0], 0, 0, 0);
;                 o[dg][1] = __builtin_amdgcn_mfma_f32_16x16x32_bf16(vf, pb[1], o[dg][1], 0, 0, 0);
;             }
	v_mfma_f32_16x16x32_bf16 v[62:65], v[180:183], v[82:85], v[62:65]
	v_lshl_add_u64 v[158:159], v[158:159], 0, s[36:37]
	v_lshl_add_u64 v[160:161], v[160:161], 0, s[14:15]
	v_mfma_f32_16x16x32_bf16 v[58:61], v[180:183], v[78:81], v[58:61]
	s_cmp_lg_u32 s27, s29
	ds_read_b64_tr_b16 v[180:181], v163 offset:37472
	ds_read_b64_tr_b16 v[182:183], v163 offset:39776
	s_waitcnt lgkmcnt(12)
	v_mfma_f32_16x16x32_bf16 v[70:73], v[184:187], v[82:85], v[70:73]
	v_mfma_f32_16x16x32_bf16 v[6:9], v[184:187], v[78:81], v[6:9]
	ds_read_b64_tr_b16 v[184:185], v163 offset:41984
	ds_read_b64_tr_b16 v[186:187], v163 offset:44288
	s_waitcnt lgkmcnt(12)
	v_mfma_f32_16x16x32_bf16 v[66:69], v[188:191], v[82:85], v[66:69]
	v_mfma_f32_16x16x32_bf16 v[10:13], v[188:191], v[78:81], v[10:13]
	ds_read_b64_tr_b16 v[188:189], v163 offset:42016
	ds_read_b64_tr_b16 v[190:191], v163 offset:44320
	s_waitcnt lgkmcnt(12)
	v_mfma_f32_16x16x32_bf16 v[74:77], v[192:195], v[82:85], v[74:77]
	v_cvt_pk_bf16_f32 v82, v172, v173
	v_cvt_pk_bf16_f32 v83, v174, v175
	v_cvt_pk_bf16_f32 v84, v176, v177
	v_mfma_f32_16x16x32_bf16 v[2:5], v[192:195], v[78:81], v[2:5]
	v_cvt_pk_bf16_f32 v78, v136, v137
	v_cvt_pk_bf16_f32 v79, v138, v139
	v_cvt_pk_bf16_f32 v80, v140, v141
	v_cvt_pk_bf16_f32 v81, v164, v165
	v_cvt_pk_bf16_f32 v85, v178, v179
	ds_read_b64_tr_b16 v[192:193], v163 offset:42048
	ds_read_b64_tr_b16 v[194:195], v163 offset:44352
	s_waitcnt lgkmcnt(12)
	v_mfma_f32_16x16x32_bf16 v[62:65], v[196:199], v[78:81], v[62:65]
	v_mfma_f32_16x16x32_bf16 v[58:61], v[196:199], v[82:85], v[58:61]
	ds_read_b64_tr_b16 v[196:197], v163 offset:42080
	ds_read_b64_tr_b16 v[198:199], v163 offset:44384
	s_waitcnt lgkmcnt(12)
	v_mfma_f32_16x16x32_bf16 v[74:77], v[200:203], v[78:81], v[74:77]
	v_mfma_f32_16x16x32_bf16 v[2:5], v[200:203], v[82:85], v[2:5]
	ds_read_b64_tr_b16 v[200:201], v163 offset:46592
	ds_read_b64_tr_b16 v[202:203], v163 offset:48896
	s_waitcnt lgkmcnt(12)
	v_mfma_f32_16x16x32_bf16 v[70:73], v[204:207], v[78:81], v[70:73]
	v_mfma_f32_16x16x32_bf16 v[6:9], v[204:207], v[82:85], v[6:9]
	ds_read_b64_tr_b16 v[204:205], v163 offset:46624
	ds_read_b64_tr_b16 v[206:207], v163 offset:48928
	s_waitcnt lgkmcnt(12)
	v_mfma_f32_16x16x32_bf16 v[10:13], v[180:183], v[82:85], v[10:13]
	v_cvt_pk_bf16_f32 v82, v86, v87
	v_cvt_pk_bf16_f32 v83, v88, v89
	v_mfma_f32_16x16x32_bf16 v[66:69], v[180:183], v[78:81], v[66:69]
	v_cvt_pk_bf16_f32 v78, v130, v131
	v_cvt_pk_bf16_f32 v79, v132, v133
	v_cvt_pk_bf16_f32 v80, v134, v135
	v_cvt_pk_bf16_f32 v81, v127, v129
	v_cvt_pk_bf16_f32 v84, v90, v91
	v_cvt_pk_bf16_f32 v85, v126, v128
	ds_read_b64_tr_b16 v[180:181], v163 offset:46656
	ds_read_b64_tr_b16 v[182:183], v163 offset:48960
	s_waitcnt lgkmcnt(12)
	v_mfma_f32_16x16x32_bf16 v[62:65], v[184:187], v[78:81], v[62:65]
	v_mfma_f32_16x16x32_bf16 v[58:61], v[184:187], v[82:85], v[58:61]
	ds_read_b64_tr_b16 v[184:185], v163 offset:46688
	ds_read_b64_tr_b16 v[186:187], v163 offset:48992
	s_waitcnt lgkmcnt(12)
	v_mfma_f32_16x16x32_bf16 v[74:77], v[188:191], v[78:81], v[74:77]
	v_mfma_f32_16x16x32_bf16 v[2:5], v[188:191], v[82:85], v[2:5]
	s_waitcnt lgkmcnt(10)
	v_mfma_f32_16x16x32_bf16 v[70:73], v[192:195], v[78:81], v[70:73]
	v_mfma_f32_16x16x32_bf16 v[6:9], v[192:195], v[82:85], v[6:9]
	s_waitcnt lgkmcnt(8)
	v_mfma_f32_16x16x32_bf16 v[66:69], v[196:199], v[78:81], v[66:69]
	v_cvt_pk_bf16_f32 v78, v111, v115
	v_cvt_pk_bf16_f32 v79, v113, v119
	v_cvt_pk_bf16_f32 v80, v117, v123
	v_mfma_f32_16x16x32_bf16 v[10:13], v[196:199], v[82:85], v[10:13]
	v_cvt_pk_bf16_f32 v81, v121, v125
	v_cvt_pk_bf16_f32 v82, v110, v114
	v_cvt_pk_bf16_f32 v83, v112, v118
	v_cvt_pk_bf16_f32 v84, v116, v122
	v_cvt_pk_bf16_f32 v85, v120, v124
	s_waitcnt lgkmcnt(6)
	v_mfma_f32_16x16x32_bf16 v[62:65], v[200:203], v[78:81], v[62:65]
	v_mfma_f32_16x16x32_bf16 v[58:61], v[200:203], v[82:85], v[58:61]
	s_waitcnt lgkmcnt(4)
	v_mfma_f32_16x16x32_bf16 v[74:77], v[204:207], v[78:81], v[74:77]
	v_mfma_f32_16x16x32_bf16 v[2:5], v[204:207], v[82:85], v[2:5]
	s_waitcnt lgkmcnt(2)
	v_mfma_f32_16x16x32_bf16 v[70:73], v[180:183], v[78:81], v[70:73]
	v_mfma_f32_16x16x32_bf16 v[6:9], v[180:183], v[82:85], v[6:9]
	s_waitcnt lgkmcnt(0)
	v_mfma_f32_16x16x32_bf16 v[66:69], v[184:187], v[78:81], v[66:69]
	v_mfma_f32_16x16x32_bf16 v[10:13], v[184:187], v[82:85], v[10:13]
	s_cbranch_scc0 .LBB0_834
	v_xor_b32_e32 v1, 0x10000, v1
	v_xor_b32_e32 v143, 0x10000, v143
	s_waitcnt vmcnt(2)
	ds_write_b128 v1, v[42:45]
	ds_write_b128 v1, v[38:41] offset:64
	ds_write_b128 v1, v[46:49] offset:128
	s_waitcnt vmcnt(1)
	ds_write_b128 v143, v[50:53] offset:32768
	s_waitcnt vmcnt(0)
	ds_write_b128 v143, v[54:57] offset:41984
	v_xor_b32_e32 v162, 0x10000, v162
	v_xor_b32_e32 v163, 0x10000, v163
	s_waitcnt lgkmcnt(0)
	s_barrier

; #define LASP __attribute__((address_space(3)))
; template <int DQK>
; __device__ __forceinline__ void flash_item(unsigned char* smem, const bf16_t* Q, int qs, const bf16_t* K0, const bf16_t* V0, int n0, const bf16_t* K1, const bf16_t* V1, int n1, int ks, int vs, bf16_t* Oo, int os, float shift) {
;     ...
;         for (int kk = 0; kk < NKK; ++kk) qf[qg][kk] = *(const bf16x8_t*)(Q + (size_t)(wave * 32 + qg * 16 + fr) * qs + kk * 32 + fq * 8);
;     f32x4_t o[4][2];
; #pragma unroll
;     for (int dg = 0; dg < 4; ++dg) { o[dg][0] = (f32x4_t){0.f, 0.f, 0.f, 0.f}; o[dg][1] = (f32x4_t){0.f, 0.f, 0.f, 0.f}; }
;     float lsum[2] = {0.f, 0.f};
;     const float nsh = -shift;
;     const int ntiles = (n0 + n1) / KT;
;     u32x4_t kreg[NKC], vreg[NVC];
;     ...
;     FL_LOAD(0);
;     for (int t = 0; t < ntiles; ++t) {
;         __syncthreads();
; #pragma unroll
;         for (int c = 0; c < NKC; ++c) *(LASP u32x4_t*)(ls + (tid >> 2) * KR + ((tid & 3) + 4 * c) * 16) = kreg[c];
; #pragma unroll
;         for (int c = 0; c < NVC; ++c) *(LASP u32x4_t*)(ls + VOFF + ((tid >> 3) + 64 * c) * VR + (tid & 7) * 16) = vreg[c];
;         __syncthreads();
;         f32x4_t s[NKG][2];
; #pragma unroll
;         for (int kg = 0; kg < NKG; ++kg) { s[kg][0] = (f32x4_t){nsh, nsh, nsh, nsh}; s[kg][1] = (f32x4_t){nsh, nsh, nsh, nsh}; }
; #pragma unroll
;         for (int kk = 0; kk < NKK; ++kk) {
; #pragma unroll
;             for (int kg = 0; kg < NKG; ++kg) {
;                 const bf16x8_t kf = *(const LASP bf16x8_t*)(ls + (kg * 16 + fr) * KR + (kk * 32 + fq * 8) * 2);
;                 s[kg][0] = __builtin_amdgcn_mfma_f32_16x16x32_bf16(kf, qf[0][kk], s[kg][0], 0, 0, 0);
;                 s[kg][1] = __builtin_amdgcn_mfma_f32_16x16x32_bf16(kf, qf[1][kk], s[kg][1], 0, 0, 0);
; __device__ __forceinline__ void p4_attn(const Params& P, int l, bool last, unsigned char* smem) {
;     ...
;             } else if (i >= 204) {
;                 const int bh = q * 12 + (i - 204), b = bh / 6, h = bh % 6;
;                 const size_t c0 = (size_t)NLAT + b * CTXL;
;                 flash_item<64>(smem, U + c0 * NINP + OQ + h * 64, NINP, U + c0 * NINP + OKK + h * 64, U + c0 * NINP + OV + h * 64, CTXL, nullptr, nullptr, 0, NINP, NINP, O + c0 * OW + h * 64, OW, shift_nac);
.LBB0_835:
	s_and_b64 vcc, exec, s[2:3]
	s_cbranch_vccz .LBB0_837
	s_add_i32 s2, s11, s13
	s_mul_hi_u32 s3, s2, 0xaaaaaaab
	s_lshr_b32 s3, s3, 2
	s_mul_i32 s5, s3, 6
	s_lshl_b32 s3, s3, 8
	s_add_i32 s3, s3, 0x8000
	s_sub_i32 s2, s2, s5
	s_mul_i32 s16, s3, 0x1200
	s_mul_hi_u32 s5, s3, 0x1200
	s_add_u32 s16, s68, s16
	s_addc_u32 s5, s69, s5
	s_lshl_b32 s2, s2, 7
	s_add_u32 s16, s16, s2
	v_mov_b32_e32 v70, v253
	s_addc_u32 s17, s5, 0
	v_mov_b64_e32 v[2:3], s[16:17]
	v_lshlrev_b32_e32 v1, 3, v70
	s_waitcnt vmcnt(9)
	v_ashrrev_i32_e32 v36, 2, v70
	v_and_b32_e32 v124, 24, v1
	v_mad_i64_i32 v[2:3], s[18:19], v36, s90, v[2:3]
	v_lshlrev_b32_e32 v4, 1, v124
	v_mov_b32_e32 v5, v0
	v_lshlrev_b32_e32 v37, 4, v70
	v_lshl_add_u64 v[58:59], v[2:3], 0, v[4:5]
	v_and_b32_e32 v2, 0x70, v37
	v_mov_b32_e32 v3, v0
	global_load_dwordx4 v[18:21], v[58:59], off offset:768
	global_load_dwordx4 v[22:25], v[58:59], off offset:832
	v_ashrrev_i32_e32 v64, 3, v70
	v_lshl_add_u64 v[60:61], s[16:17], 0, v[2:3]
	v_mad_i64_i32 v[4:5], s[18:19], v64, s90, v[60:61]
	v_add_u32_e32 v65, 64, v64
	global_load_dwordx4 v[26:29], v[4:5], off offset:1536
	v_mad_i64_i32 v[4:5], s[18:19], v65, s90, v[60:61]
	global_load_dwordx4 v[30:33], v[4:5], off offset:1536
	v_and_b32_e32 v3, 15, v70
	v_bfe_u32 v1, v70, 4, 2
	v_ashrrev_i32_e32 v4, 1, v70
	v_mov_b32_e32 v216, v211
	v_and_or_b32 v211, v4, s95, v3
	v_lshlrev_b32_e32 v4, 4, v1
	v_mov_b32_e32 v5, v0
	v_lshl_add_u64 v[6:7], s[16:17], 0, v[4:5]
	v_or_b32_e32 v227, 16, v211
	v_mad_i64_i32 v[8:9], s[16:17], v211, s90, v[6:7]
	v_mad_i64_i32 v[34:35], s[16:17], v227, s90, v[6:7]
	global_load_dwordx4 v[10:13], v[8:9], off
	global_load_dwordx4 v[14:17], v[34:35], off
	v_mul_lo_u32 v5, v36, s89
	v_and_b32_e32 v6, 48, v37
	v_mul_lo_u32 v7, v64, s89
	v_mul_u32_u24_e32 v3, 0x90, v3
	v_add3_u32 v63, 0, v5, v6
	v_add3_u32 v62, 0, v2, v7
	v_add3_u32 v71, 0, v4, v3
	global_load_dwordx4 v[6:9], v[8:9], off offset:64
	s_nop 0
	global_load_dwordx4 v[2:5], v[34:35], off offset:64
	s_barrier
	s_mov_b64 s[16:17], 0x90600
	v_lshl_add_u64 v[60:61], v[60:61], 0, s[16:17]
	v_mad_i64_i32 v[146:147], s[16:17], v65, s90, v[60:61]
	s_mov_b32 s5, 0x90000
	v_lshlrev_b32_e32 v204, 3, v1
	v_mov_b32_e32 v205, v0
	s_waitcnt vmcnt(7)
	ds_write_b128 v63, v[18:21]
	s_waitcnt vmcnt(6)
	ds_write_b128 v63, v[22:25] offset:64
	s_waitcnt vmcnt(5)
	ds_write_b128 v62, v[26:29] offset:32768
	s_waitcnt vmcnt(4)
	ds_write_b128 v62, v[30:33] offset:41984
	s_waitcnt lgkmcnt(0)
	s_barrier
	ds_read_b128 v[54:57], v71 offset:9216
	v_mov_b64_e32 v[18:19], s[48:49]
	v_mov_b64_e32 v[20:21], s[50:51]
	ds_read_b128 v[22:25], v71
	ds_read_b128 v[30:33], v71 offset:2304
	s_waitcnt vmcnt(3) lgkmcnt(2)
	v_mfma_f32_16x16x32_bf16 v[66:69], v[54:57], v[10:13], v[18:21]
	ds_read_b128 v[38:41], v71 offset:4608
	ds_read_b128 v[46:49], v71 offset:6912
	s_waitcnt vmcnt(2)
	v_mfma_f32_16x16x32_bf16 v[72:75], v[54:57], v[14:17], v[18:21]
	ds_read_b128 v[54:57], v71 offset:11520
	s_waitcnt lgkmcnt(0)
	v_mfma_f32_16x16x32_bf16 v[76:79], v[54:57], v[10:13], v[18:21]
	v_mfma_f32_16x16x32_bf16 v[80:83], v[54:57], v[14:17], v[18:21]
	ds_read_b128 v[54:57], v71 offset:13824
	s_waitcnt lgkmcnt(0)
	v_mfma_f32_16x16x32_bf16 v[84:87], v[54:57], v[10:13], v[18:21]
	v_mfma_f32_16x16x32_bf16 v[88:91], v[54:57], v[14:17], v[18:21]
	ds_read_b128 v[54:57], v71 offset:16128
	s_waitcnt lgkmcnt(0)
	v_mfma_f32_16x16x32_bf16 v[92:95], v[54:57], v[10:13], v[18:21]
	v_mfma_f32_16x16x32_bf16 v[96:99], v[54:57], v[14:17], v[18:21]
	ds_read_b128 v[54:57], v71 offset:64
	v_mfma_f32_16x16x32_bf16 v[26:29], v[22:25], v[10:13], v[18:21]
	v_mfma_f32_16x16x32_bf16 v[22:25], v[22:25], v[14:17], v[18:21]
	s_waitcnt vmcnt(0) lgkmcnt(0)
	v_mfma_f32_16x16x32_bf16 v[104:107], v[54:57], v[2:5], v[22:25]
	v_mfma_f32_16x16x32_bf16 v[34:37], v[30:33], v[10:13], v[18:21]
	s_nop 4
	ds_read_b128 v[22:25], v71 offset:2368
	s_nop 0
	v_exp_f32_e32 v196, v105
	v_exp_f32_e32 v198, v106
	v_mfma_f32_16x16x32_bf16 v[30:33], v[30:33], v[14:17], v[18:21]
	v_exp_f32_e32 v188, v107
	s_nop 0
	v_cvt_pk_bf16_f32 v107, v198, v188
	s_waitcnt lgkmcnt(0)
	v_mfma_f32_16x16x32_bf16 v[108:111], v[22:25], v[6:9], v[34:37]
	v_mfma_f32_16x16x32_bf16 v[112:115], v[22:25], v[2:5], v[30:33]
	ds_read_b128 v[22:25], v71 offset:4672
	s_nop 5
	v_exp_f32_e32 v160, v108
	v_exp_f32_e32 v158, v109
	v_mfma_f32_16x16x32_bf16 v[42:45], v[38:41], v[10:13], v[18:21]
	v_bfe_u32 v30, v70, 2, 2
	v_exp_f32_e32 v164, v110
	v_exp_f32_e32 v162, v111
	v_mfma_f32_16x16x32_bf16 v[38:41], v[38:41], v[14:17], v[18:21]
	v_exp_f32_e32 v192, v112
	v_exp_f32_e32 v190, v113
	v_exp_f32_e32 v194, v114
	v_mfma_f32_16x16x32_bf16 v[100:103], v[54:57], v[6:9], v[26:29]
	v_exp_f32_e32 v200, v115
	v_cvt_pk_bf16_f32 v105, v164, v162
	v_cvt_pk_bf16_f32 v108, v192, v190
	s_waitcnt lgkmcnt(0)
	v_mfma_f32_16x16x32_bf16 v[116:119], v[22:25], v[6:9], v[42:45]
	v_cvt_pk_bf16_f32 v109, v194, v200
	s_nop 1
	v_exp_f32_e32 v142, v101
	v_exp_f32_e32 v156, v102
	v_mfma_f32_16x16x32_bf16 v[54:57], v[22:25], v[2:5], v[38:41]
	ds_read_b128 v[22:25], v71 offset:6976
	v_exp_f32_e32 v144, v103
	v_exp_f32_e32 v170, v116
	v_mfma_f32_16x16x32_bf16 v[50:53], v[46:49], v[10:13], v[18:21]
	v_cvt_pk_bf16_f32 v103, v156, v144
	s_nop 2
	v_exp_f32_e32 v202, v54
	v_mfma_f32_16x16x32_bf16 v[46:49], v[46:49], v[14:17], v[18:21]
	v_exp_f32_e32 v186, v55
	v_exp_f32_e32 v178, v56
	v_exp_f32_e32 v176, v57
	s_waitcnt lgkmcnt(0)
	v_mfma_f32_16x16x32_bf16 v[120:123], v[22:25], v[6:9], v[50:53]
	v_cvt_pk_bf16_f32 v138, v202, v186
	v_cvt_pk_bf16_f32 v139, v178, v176
	v_mfma_f32_16x16x32_bf16 v[50:53], v[22:25], v[2:5], v[46:49]
	ds_read_b128 v[22:25], v71 offset:9280
	s_waitcnt lgkmcnt(0)
; #define LASP __attribute__((address_space(3)))
; template <int DQK>
; __device__ __forceinline__ void flash_item(unsigned char* smem, const bf16_t* Q, int qs, const bf16_t* K0, const bf16_t* V0, int n0, const bf16_t* K1, const bf16_t* V1, int n1, int ks, int vs, bf16_t* Oo, int os, float shift) {
;     ...
;         for (int kk = 0; kk < NKK; ++kk) {
; #pragma unroll
;             for (int kg = 0; kg < NKG; ++kg) {
;                 const bf16x8_t kf = *(const LASP bf16x8_t*)(ls + (kg * 16 + fr) * KR + (kk * 32 + fq * 8) * 2);
;                 s[kg][0] = __builtin_amdgcn_mfma_f32_16x16x32_bf16(kf, qf[0][kk], s[kg][0], 0, 0, 0);
;                 s[kg][1] = __builtin_amdgcn_mfma_f32_16x16x32_bf16(kf, qf[1][kk], s[kg][1], 0, 0, 0);
;             }
;             asm volatile("" ::: "memory");
;         }
;         if (t + 1 < ntiles) FL_LOAD((t + 1) * KT);
; #pragma unroll
;         for (int qg = 0; qg < 2; ++qg) {
;             float ps = 0.f;
; #pragma unroll
;             for (int kg = 0; kg < NKG; ++kg)
; #pragma unroll
;                 for (int j = 0; j < 4; ++j) { const float p = __builtin_amdgcn_exp2f(s[kg][qg][j]); s[kg][qg][j] = p; ps += p; }
;             lsum[qg] += ps;
;         }
; #pragma unroll
;         for (int kp = 0; kp < NKP; ++kp) {
;             bf16x8_t pb[2];
; #pragma unroll
;             for (int qg = 0; qg < 2; ++qg) {
;                 const f32x4_t a = s[2 * kp][qg], b = s[2 * kp + 1][qg];
;                 u32x4_t pk; pk.x = pg8::cvt_pk_bf16(a[0], a[1]); pk.y = pg8::cvt_pk_bf16(a[2], a[3]); pk.z = pg8::cvt_pk_bf16(b[0], b[1]); pk.w = pg8::cvt_pk_bf16(b[2], b[3]);
;                 pb[qg] = __builtin_bit_cast(bf16x8_t, pk);
;             }
; #pragma unroll
;             for (int dg = 0; dg < 4; ++dg) {
;                 LASP unsigned char* va = ls + VOFF + (32 * kp + 4 * fq + (fr >> 2)) * VR + (16 * dg + 4 * (fr & 3)) * 2;
;                 const s16x4 v0 = __builtin_amdgcn_ds_read_tr16_b64_v4i16((LASP s16x4*)va);
;                 const s16x4 v1 = __builtin_amdgcn_ds_read_tr16_b64_v4i16((LASP s16x4*)(va + 16 * VR));
;                 const bf16x8_t vf = __builtin_shufflevector(v0, v1, 0, 1, 2, 3, 4, 5, 6, 7);
;                 o[dg][0] = __builtin_amdgcn_mfma_f32_16x16x32_bf16(vf, pb[0], o[dg][0], 0, 0, 0);
;                 o[dg][1] = __builtin_amdgcn_mfma_f32_16x16x32_bf16(vf, pb[1], o[dg][1], 0, 0, 0);
;             }
	v_mfma_f32_16x16x32_bf16 v[66:69], v[22:25], v[6:9], v[66:69]
	s_nop 4
	v_exp_f32_e32 v180, v50
	v_exp_f32_e32 v174, v51
	v_exp_f32_e32 v128, v53
	v_mfma_f32_16x16x32_bf16 v[42:45], v[22:25], v[2:5], v[72:75]
	ds_read_b128 v[22:25], v71 offset:11584
	v_exp_f32_e32 v70, v67
	v_cvt_pk_bf16_f32 v140, v180, v174
	s_waitcnt lgkmcnt(0)
	v_mfma_f32_16x16x32_bf16 v[46:49], v[22:25], v[6:9], v[76:79]
	v_lshl_or_b32 v74, v1, 2, v30
	v_exp_f32_e32 v73, v100
	v_exp_f32_e32 v72, v68
	v_mfma_f32_16x16x32_bf16 v[38:41], v[22:25], v[2:5], v[80:83]
	ds_read_b128 v[22:25], v71 offset:13888
	v_exp_f32_e32 v75, v104
	v_exp_f32_e32 v76, v117
	s_waitcnt lgkmcnt(0)
	v_mfma_f32_16x16x32_bf16 v[34:37], v[22:25], v[6:9], v[84:87]
	v_exp_f32_e32 v80, v118
	v_exp_f32_e32 v78, v119
	s_nop 0
	v_exp_f32_e32 v84, v120
	v_mfma_f32_16x16x32_bf16 v[26:29], v[22:25], v[2:5], v[88:91]
	ds_read_b128 v[22:25], v71 offset:16192
	v_exp_f32_e32 v82, v121
	s_waitcnt lgkmcnt(0)
	v_mfma_f32_16x16x32_bf16 v[30:33], v[22:25], v[6:9], v[92:95]
	v_exp_f32_e32 v88, v122
	v_exp_f32_e32 v86, v123
	v_cvt_pk_bf16_f32 v102, v73, v142
	v_mfma_f32_16x16x32_bf16 v[22:25], v[22:25], v[2:5], v[96:99]
	v_cvt_pk_bf16_f32 v104, v160, v158
	v_exp_f32_e32 v118, v52
	v_cvt_pk_bf16_f32 v106, v75, v196
	v_exp_f32_e32 v96, v66
	v_mul_u32_u24_e32 v66, 0x90, v74
	v_add3_u32 v226, 0, v124, v66
	ds_read_b64_tr_b16 v[92:93], v226 offset:35072
	ds_read_b64_tr_b16 v[90:91], v226 offset:32768
	ds_read_b64_tr_b16 v[110:111], v226 offset:32800
	ds_read_b64_tr_b16 v[112:113], v226 offset:35104
	v_exp_f32_e32 v74, v69
	ds_read_b64_tr_b16 v[66:67], v226 offset:32832
	ds_read_b64_tr_b16 v[68:69], v226 offset:35136
	ds_read_b64_tr_b16 v[130:131], v226 offset:32864
	ds_read_b64_tr_b16 v[132:133], v226 offset:35168
	ds_read_b64_tr_b16 v[50:51], v226 offset:37376
	ds_read_b64_tr_b16 v[52:53], v226 offset:39680
	s_waitcnt lgkmcnt(8)
	v_mfma_f32_16x16x32_bf16 v[114:117], v[90:93], v[102:105], 0
	v_exp_f32_e32 v94, v46
	v_exp_f32_e32 v100, v48
	v_cvt_pk_bf16_f32 v141, v118, v128
	v_mfma_f32_16x16x32_bf16 v[120:123], v[90:93], v[106:109], 0
	v_exp_f32_e32 v92, v47
	v_exp_f32_e32 v184, v42
	v_exp_f32_e32 v182, v43
	s_waitcnt lgkmcnt(6)
	v_mfma_f32_16x16x32_bf16 v[124:127], v[110:113], v[102:105], 0
	v_exp_f32_e32 v168, v44
	v_exp_f32_e32 v166, v45
	v_exp_f32_e32 v172, v38
	v_mfma_f32_16x16x32_bf16 v[110:113], v[110:113], v[106:109], 0
	v_exp_f32_e32 v90, v35
	v_exp_f32_e32 v98, v36
	s_waitcnt lgkmcnt(4)
	v_mfma_f32_16x16x32_bf16 v[134:137], v[66:69], v[102:105], 0
	v_mfma_f32_16x16x32_bf16 v[54:57], v[66:69], v[106:109], 0
	s_waitcnt lgkmcnt(2)
	v_mfma_f32_16x16x32_bf16 v[66:69], v[130:133], v[102:105], 0
	ds_read_b64_tr_b16 v[102:103], v226 offset:37408
	ds_read_b64_tr_b16 v[104:105], v226 offset:39712
	v_mfma_f32_16x16x32_bf16 v[130:133], v[130:133], v[106:109], 0
	v_cvt_pk_bf16_f32 v106, v170, v76
	v_cvt_pk_bf16_f32 v107, v80, v78
	v_cvt_pk_bf16_f32 v108, v84, v82
	v_cvt_pk_bf16_f32 v109, v88, v86
	s_waitcnt lgkmcnt(0)
	v_mfma_f32_16x16x32_bf16 v[110:113], v[102:105], v[138:141], v[110:113]
	v_mfma_f32_16x16x32_bf16 v[228:231], v[50:53], v[106:109], v[114:117]
	s_nop 2
	v_exp_f32_e32 v116, v49
	ds_read_b64_tr_b16 v[46:47], v226 offset:37440
	ds_read_b64_tr_b16 v[48:49], v226 offset:39744
	ds_read_b64_tr_b16 v[232:233], v226 offset:37472
	ds_read_b64_tr_b16 v[234:235], v226 offset:39776
	v_mfma_f32_16x16x32_bf16 v[50:53], v[50:53], v[138:141], v[120:123]
	v_exp_f32_e32 v114, v37
	v_mfma_f32_16x16x32_bf16 v[120:123], v[102:105], v[106:109], v[124:127]
	v_exp_f32_e32 v104, v39
	v_exp_f32_e32 v102, v40
	v_mov_b32_e32 v103, v222
	s_waitcnt lgkmcnt(2)
	v_mfma_f32_16x16x32_bf16 v[134:137], v[46:49], v[106:109], v[134:137]
	v_exp_f32_e32 v126, v34
	v_exp_f32_e32 v124, v30
	v_mfma_f32_16x16x32_bf16 v[42:45], v[46:49], v[138:141], v[54:57]
	s_waitcnt lgkmcnt(0)
	v_mfma_f32_16x16x32_bf16 v[46:49], v[232:235], v[106:109], v[66:69]
	v_exp_f32_e32 v106, v41
	ds_read_b64_tr_b16 v[38:39], v226 offset:41984
	ds_read_b64_tr_b16 v[40:41], v226 offset:44288
	v_cvt_pk_bf16_f32 v66, v96, v70
	v_mfma_f32_16x16x32_bf16 v[54:57], v[232:235], v[138:141], v[130:133]
	ds_read_b64_tr_b16 v[138:139], v226 offset:42016
	ds_read_b64_tr_b16 v[140:141], v226 offset:44320
	ds_read_b64_tr_b16 v[34:35], v226 offset:42048
	ds_read_b64_tr_b16 v[36:37], v226 offset:44352
	v_cvt_pk_bf16_f32 v67, v72, v74
	v_cvt_pk_bf16_f32 v68, v94, v92
	v_cvt_pk_bf16_f32 v69, v100, v116
	v_cvt_pk_bf16_f32 v232, v184, v182
	v_cvt_pk_bf16_f32 v233, v168, v166
	v_cvt_pk_bf16_f32 v234, v172, v104
	v_cvt_pk_bf16_f32 v235, v102, v106
	s_waitcnt lgkmcnt(2)
	v_mfma_f32_16x16x32_bf16 v[236:239], v[138:141], v[66:69], v[120:123]
	v_exp_f32_e32 v130, v32
	v_exp_f32_e32 v132, v33
	v_exp_f32_e32 v108, v23
	v_exp_f32_e32 v122, v31
	ds_read_b64_tr_b16 v[30:31], v226 offset:42080
	ds_read_b64_tr_b16 v[32:33], v226 offset:44384
	s_waitcnt lgkmcnt(2)
	v_mfma_f32_16x16x32_bf16 v[244:247], v[34:37], v[66:69], v[134:137]
	v_exp_f32_e32 v120, v24
	v_mfma_f32_16x16x32_bf16 v[34:37], v[34:37], v[232:235], v[42:45]
	s_nop 2
	ds_read_b64_tr_b16 v[42:43], v226 offset:46592
	ds_read_b64_tr_b16 v[44:45], v226 offset:48896
	v_exp_f32_e32 v136, v27
	v_exp_f32_e32 v134, v28
	v_mfma_f32_16x16x32_bf16 v[228:231], v[38:41], v[66:69], v[228:231]
	v_mfma_f32_16x16x32_bf16 v[240:243], v[138:141], v[232:235], v[110:113]
	v_exp_f32_e32 v140, v26
	v_exp_f32_e32 v138, v29
	s_nop 0
	v_exp_f32_e32 v110, v22
	v_exp_f32_e32 v112, v25
	v_mfma_f32_16x16x32_bf16 v[38:41], v[38:41], v[232:235], v[50:53]
	s_waitcnt lgkmcnt(2)
; template <int DQK>
; __device__ __forceinline__ void flash_item(unsigned char* smem, const bf16_t* Q, int qs, const bf16_t* K0, const bf16_t* V0, int n0, const bf16_t* K1, const bf16_t* V1, int n1, int ks, int vs, bf16_t* Oo, int os, float shift) {
;     ...
;     for (int t = 0; t < ntiles; ++t) {
;         __syncthreads();
; #pragma unroll
;         for (int c = 0; c < NKC; ++c) *(LASP u32x4_t*)(ls + (tid >> 2) * KR + ((tid & 3) + 4 * c) * 16) = kreg[c];
; #pragma unroll
;         for (int c = 0; c < NVC; ++c) *(LASP u32x4_t*)(ls + VOFF + ((tid >> 3) + 64 * c) * VR + (tid & 7) * 16) = vreg[c];
;         __syncthreads();
;         f32x4_t s[NKG][2];
; #pragma unroll
;         for (int kg = 0; kg < NKG; ++kg) { s[kg][0] = (f32x4_t){nsh, nsh, nsh, nsh}; s[kg][1] = (f32x4_t){nsh, nsh, nsh, nsh}; }
; #pragma unroll
;         for (int kk = 0; kk < NKK; ++kk) {
; #pragma unroll
;             for (int kg = 0; kg < NKG; ++kg) {
;                 const bf16x8_t kf = *(const LASP bf16x8_t*)(ls + (kg * 16 + fr) * KR + (kk * 32 + fq * 8) * 2);
;                 s[kg][0] = __builtin_amdgcn_mfma_f32_16x16x32_bf16(kf, qf[0][kk], s[kg][0], 0, 0, 0);
;                 s[kg][1] = __builtin_amdgcn_mfma_f32_16x16x32_bf16(kf, qf[1][kk], s[kg][1], 0, 0, 0);
;             }
;             asm volatile("" ::: "memory");
;         }
;         if (t + 1 < ntiles) FL_LOAD((t + 1) * KT);
; #pragma unroll
;         for (int qg = 0; qg < 2; ++qg) {
;             float ps = 0.f;
; #pragma unroll
;             for (int kg = 0; kg < NKG; ++kg)
; #pragma unroll
;                 for (int j = 0; j < 4; ++j) { const float p = __builtin_amdgcn_exp2f(s[kg][qg][j]); s[kg][qg][j] = p; ps += p; }
;             lsum[qg] += ps;
;         }
; #pragma unroll
;         for (int kp = 0; kp < NKP; ++kp) {
;             bf16x8_t pb[2];
; #pragma unroll
;             for (int qg = 0; qg < 2; ++qg) {
;                 const f32x4_t a = s[2 * kp][qg], b = s[2 * kp + 1][qg];
;                 u32x4_t pk; pk.x = pg8::cvt_pk_bf16(a[0], a[1]); pk.y = pg8::cvt_pk_bf16(a[2], a[3]); pk.z = pg8::cvt_pk_bf16(b[0], b[1]); pk.w = pg8::cvt_pk_bf16(b[2], b[3]);
;                 pb[qg] = __builtin_bit_cast(bf16x8_t, pk);
;             }
; #pragma unroll
;             for (int dg = 0; dg < 4; ++dg) {
;                 LASP unsigned char* va = ls + VOFF + (32 * kp + 4 * fq + (fr >> 2)) * VR + (16 * dg + 4 * (fr & 3)) * 2;
	v_mfma_f32_16x16x32_bf16 v[26:29], v[30:33], v[66:69], v[46:49]
	v_cvt_pk_bf16_f32 v66, v140, v136
	v_cvt_pk_bf16_f32 v67, v134, v138
	v_cvt_pk_bf16_f32 v68, v110, v108
	v_mfma_f32_16x16x32_bf16 v[54:57], v[30:33], v[232:235], v[54:57]
	v_cvt_pk_bf16_f32 v30, v126, v90
	v_cvt_pk_bf16_f32 v31, v98, v114
	v_cvt_pk_bf16_f32 v32, v124, v122
	v_cvt_pk_bf16_f32 v33, v130, v132
	v_cvt_pk_bf16_f32 v69, v120, v112
	s_waitcnt lgkmcnt(0)
	v_mfma_f32_16x16x32_bf16 v[46:49], v[42:45], v[30:33], v[228:231]
	ds_read_b64_tr_b16 v[22:23], v226 offset:46624
	ds_read_b64_tr_b16 v[24:25], v226 offset:48928
	s_nop 0
	ds_read_b64_tr_b16 v[228:229], v226 offset:46656
	ds_read_b64_tr_b16 v[230:231], v226 offset:48960
	v_mfma_f32_16x16x32_bf16 v[50:53], v[42:45], v[66:69], v[38:41]
	s_waitcnt lgkmcnt(2)
	v_mfma_f32_16x16x32_bf16 v[38:41], v[22:25], v[30:33], v[236:239]
	v_mfma_f32_16x16x32_bf16 v[42:45], v[22:25], v[66:69], v[240:243]
	v_mad_i64_i32 v[22:23], s[16:17], v64, s90, v[60:61]
	s_mov_b64 s[16:17], 0x90300
	s_nop 0
	v_lshl_add_u64 v[64:65], v[58:59], 0, s[16:17]
	v_add_co_u32_e32 v58, vcc, s5, v58
	global_load_dwordx4 v[232:235], v[22:23], off
	s_nop 0
	v_addc_co_u32_e32 v59, vcc, 0, v59, vcc
	s_waitcnt lgkmcnt(0)
	v_mfma_f32_16x16x32_bf16 v[22:25], v[228:231], v[30:33], v[244:247]
	ds_read_b64_tr_b16 v[236:237], v226 offset:46688
	ds_read_b64_tr_b16 v[238:239], v226 offset:48992
	s_mul_hi_u32 s5, s3, 0xa00
	s_mulk_i32 s3, 0xa00
	v_mfma_f32_16x16x32_bf16 v[34:37], v[228:231], v[66:69], v[34:37]
	global_load_dwordx4 v[58:61], v[58:59], off offset:768
	s_nop 0
	global_load_dwordx4 v[228:231], v[64:65], off offset:64
	global_load_dwordx4 v[240:243], v[146:147], off
	s_waitcnt lgkmcnt(0)
	v_mfma_f32_16x16x32_bf16 v[30:33], v[236:239], v[30:33], v[26:29]
	s_barrier
	s_waitcnt vmcnt(2)
	ds_write_b128 v63, v[58:61]
	s_waitcnt vmcnt(1)
	ds_write_b128 v63, v[228:231] offset:64
	ds_write_b128 v62, v[232:235] offset:32768
	s_waitcnt vmcnt(0)
	ds_write_b128 v62, v[240:243] offset:41984
	v_mfma_f32_16x16x32_bf16 v[26:29], v[236:239], v[66:69], v[54:57]
	s_waitcnt lgkmcnt(0)
	s_barrier
	s_nop 0
	ds_read_b128 v[54:57], v71
	ds_read_b128 v[62:65], v71 offset:2304
	s_waitcnt lgkmcnt(0)
	v_mfma_f32_16x16x32_bf16 v[66:69], v[62:65], v[10:13], v[18:21]
	s_add_u32 s3, s66, s3
	s_addc_u32 s5, s67, s5
	s_add_u32 s2, s3, s2
	v_mfma_f32_16x16x32_bf16 v[228:231], v[62:65], v[14:17], v[18:21]
	ds_read_b128 v[62:65], v71 offset:4608
	s_addc_u32 s3, s5, 0
	s_waitcnt lgkmcnt(0)
	v_mfma_f32_16x16x32_bf16 v[232:235], v[62:65], v[10:13], v[18:21]
	v_mfma_f32_16x16x32_bf16 v[236:239], v[62:65], v[14:17], v[18:21]
	ds_read_b128 v[62:65], v71 offset:6912
	s_waitcnt lgkmcnt(0)
	v_mfma_f32_16x16x32_bf16 v[240:243], v[62:65], v[10:13], v[18:21]
	v_mfma_f32_16x16x32_bf16 v[244:247], v[62:65], v[14:17], v[18:21]
	ds_read_b128 v[62:65], v71 offset:9216
	s_waitcnt lgkmcnt(0)
	v_mfma_f32_16x16x32_bf16 v[248:251], v[62:65], v[10:13], v[18:21]
	v_mfma_f32_16x16x32_bf16 v[146:149], v[62:65], v[14:17], v[18:21]
	ds_read_b128 v[62:65], v71 offset:11520
	s_waitcnt lgkmcnt(0)
	v_mfma_f32_16x16x32_bf16 v[150:153], v[62:65], v[10:13], v[18:21]
	v_mfma_f32_16x16x32_bf16 v[212:215], v[62:65], v[14:17], v[18:21]
	ds_read_b128 v[62:65], v71 offset:13824
	s_waitcnt lgkmcnt(0)
	v_mfma_f32_16x16x32_bf16 v[218:221], v[62:65], v[10:13], v[18:21]
	v_mfma_f32_16x16x32_bf16 v[206:209], v[62:65], v[14:17], v[18:21]
	ds_read_b128 v[62:65], v71 offset:16128
	v_mfma_f32_16x16x32_bf16 v[58:61], v[54:57], v[10:13], v[18:21]
	v_mfma_f32_16x16x32_bf16 v[54:57], v[54:57], v[14:17], v[18:21]
	s_waitcnt lgkmcnt(0)
	v_mfma_f32_16x16x32_bf16 v[10:13], v[62:65], v[10:13], v[18:21]
	v_mfma_f32_16x16x32_bf16 v[14:17], v[62:65], v[14:17], v[18:21]
	s_nop 2
	ds_read_b128 v[18:21], v71 offset:64
	s_waitcnt lgkmcnt(0)
	v_mfma_f32_16x16x32_bf16 v[222:225], v[18:21], v[6:9], v[58:61]
	s_nop 7
	v_exp_f32_e32 v143, v222
	v_mfma_f32_16x16x32_bf16 v[62:65], v[18:21], v[2:5], v[54:57]
	ds_read_b128 v[18:21], v71 offset:2368
	v_exp_f32_e32 v157, v223
	v_exp_f32_e32 v145, v224
	s_waitcnt lgkmcnt(0)
	v_mfma_f32_16x16x32_bf16 v[54:57], v[18:21], v[6:9], v[66:69]
	v_exp_f32_e32 v161, v225
	v_add_f32_e32 v222, 0, v75
	s_nop 0
	v_exp_f32_e32 v197, v62
	v_mfma_f32_16x16x32_bf16 v[66:69], v[18:21], v[2:5], v[228:231]
	ds_read_b128 v[18:21], v71 offset:4672
	s_nop 1
	v_exp_f32_e32 v159, v54
	v_exp_f32_e32 v165, v55
	s_waitcnt lgkmcnt(0)
	v_mfma_f32_16x16x32_bf16 v[232:235], v[18:21], v[6:9], v[232:235]
	v_exp_f32_e32 v163, v56
	v_exp_f32_e32 v171, v57
	v_exp_f32_e32 v199, v63
	v_mfma_f32_16x16x32_bf16 v[58:61], v[18:21], v[2:5], v[236:239]
	ds_read_b128 v[18:21], v71 offset:6976
	s_nop 2
	v_exp_f32_e32 v77, v232
	v_exp_f32_e32 v81, v233
	s_waitcnt lgkmcnt(0)
	v_mfma_f32_16x16x32_bf16 v[236:239], v[18:21], v[6:9], v[240:243]
	v_exp_f32_e32 v79, v234
	v_exp_f32_e32 v85, v235
	v_exp_f32_e32 v189, v64
	v_mfma_f32_16x16x32_bf16 v[228:231], v[18:21], v[2:5], v[244:247]
	ds_read_b128 v[18:21], v71 offset:9280
	s_nop 2
	v_exp_f32_e32 v83, v236
	v_exp_f32_e32 v89, v237
	s_waitcnt lgkmcnt(0)
	v_mfma_f32_16x16x32_bf16 v[240:243], v[18:21], v[6:9], v[248:251]
	v_exp_f32_e32 v87, v238
	v_exp_f32_e32 v97, v239
	v_exp_f32_e32 v193, v65
	v_mfma_f32_16x16x32_bf16 v[18:21], v[18:21], v[2:5], v[146:149]
	s_nop 3
	v_exp_f32_e32 v75, v242
	v_exp_f32_e32 v95, v243
	v_mov_b32_e32 v223, v0
	ds_read_b128 v[146:149], v71 offset:11584
	s_waitcnt lgkmcnt(0)
	v_mfma_f32_16x16x32_bf16 v[244:247], v[146:149], v[6:9], v[150:153]
	v_exp_f32_e32 v191, v66
	v_exp_f32_e32 v195, v67
	v_exp_f32_e32 v201, v68
	v_mfma_f32_16x16x32_bf16 v[150:153], v[146:149], v[2:5], v[212:215]
	ds_read_b128 v[146:149], v71 offset:13888
	s_nop 2
	v_exp_f32_e32 v93, v244
	v_exp_f32_e32 v101, v245
	s_waitcnt lgkmcnt(0)
; #define LASP __attribute__((address_space(3)))
; template <int DQK>
; __device__ __forceinline__ void flash_item(unsigned char* smem, const bf16_t* Q, int qs, const bf16_t* K0, const bf16_t* V0, int n0, const bf16_t* K1, const bf16_t* V1, int n1, int ks, int vs, bf16_t* Oo, int os, float shift) {
;     ...
;         f32x4_t s[NKG][2];
; #pragma unroll
;         for (int kg = 0; kg < NKG; ++kg) { s[kg][0] = (f32x4_t){nsh, nsh, nsh, nsh}; s[kg][1] = (f32x4_t){nsh, nsh, nsh, nsh}; }
; #pragma unroll
;         for (int kk = 0; kk < NKK; ++kk) {
; #pragma unroll
;             for (int kg = 0; kg < NKG; ++kg) {
;                 const bf16x8_t kf = *(const LASP bf16x8_t*)(ls + (kg * 16 + fr) * KR + (kk * 32 + fq * 8) * 2);
;                 s[kg][0] = __builtin_amdgcn_mfma_f32_16x16x32_bf16(kf, qf[0][kk], s[kg][0], 0, 0, 0);
;                 s[kg][1] = __builtin_amdgcn_mfma_f32_16x16x32_bf16(kf, qf[1][kk], s[kg][1], 0, 0, 0);
;             }
;             asm volatile("" ::: "memory");
;         }
;         if (t + 1 < ntiles) FL_LOAD((t + 1) * KT);
; #pragma unroll
;         for (int qg = 0; qg < 2; ++qg) {
;             float ps = 0.f;
; #pragma unroll
;             for (int kg = 0; kg < NKG; ++kg)
; #pragma unroll
;                 for (int j = 0; j < 4; ++j) { const float p = __builtin_amdgcn_exp2f(s[kg][qg][j]); s[kg][qg][j] = p; ps += p; }
;             lsum[qg] += ps;
;         }
; #pragma unroll
;         for (int kp = 0; kp < NKP; ++kp) {
;             bf16x8_t pb[2];
; #pragma unroll
;             for (int qg = 0; qg < 2; ++qg) {
;                 const f32x4_t a = s[2 * kp][qg], b = s[2 * kp + 1][qg];
;                 u32x4_t pk; pk.x = pg8::cvt_pk_bf16(a[0], a[1]); pk.y = pg8::cvt_pk_bf16(a[2], a[3]); pk.z = pg8::cvt_pk_bf16(b[0], b[1]); pk.w = pg8::cvt_pk_bf16(b[2], b[3]);
;                 pb[qg] = __builtin_bit_cast(bf16x8_t, pk);
;             }
; #pragma unroll
;             for (int dg = 0; dg < 4; ++dg) {
;                 LASP unsigned char* va = ls + VOFF + (32 * kp + 4 * fq + (fr >> 2)) * VR + (16 * dg + 4 * (fr & 3)) * 2;
;                 const s16x4 v0 = __builtin_amdgcn_ds_read_tr16_b64_v4i16((LASP s16x4*)va);
;                 const s16x4 v1 = __builtin_amdgcn_ds_read_tr16_b64_v4i16((LASP s16x4*)(va + 16 * VR));
;                 const bf16x8_t vf = __builtin_shufflevector(v0, v1, 0, 1, 2, 3, 4, 5, 6, 7);
	v_mfma_f32_16x16x32_bf16 v[212:215], v[146:149], v[6:9], v[218:221]
	s_nop 2
	ds_read_b128 v[218:221], v71 offset:16192
	v_exp_f32_e32 v71, v240
	v_exp_f32_e32 v117, v246
	v_mfma_f32_16x16x32_bf16 v[146:149], v[146:149], v[2:5], v[206:209]
	v_exp_f32_e32 v127, v247
	v_exp_f32_e32 v91, v212
	v_exp_f32_e32 v99, v213
	v_add_f32_e32 v206, 0, v73
	v_mov_b32_e32 v207, v0
	s_waitcnt lgkmcnt(0)
	v_mfma_f32_16x16x32_bf16 v[6:9], v[218:221], v[6:9], v[10:13]
	v_exp_f32_e32 v73, v241
	v_exp_f32_e32 v115, v214
	v_exp_f32_e32 v125, v215
	v_add_f32_e32 v10, v142, v206
	v_add_f32_e32 v11, v143, v207
	s_nop 3
	v_exp_f32_e32 v123, v6
	v_add_f32_e32 v10, v156, v10
	v_add_f32_e32 v11, v157, v11
	v_exp_f32_e32 v131, v7
	v_add_f32_e32 v10, v144, v10
	v_add_f32_e32 v11, v145, v11
	v_exp_f32_e32 v133, v8
	v_add_f32_e32 v10, v160, v10
	v_add_f32_e32 v11, v161, v11
	v_exp_f32_e32 v1, v9
	v_add_f32_e32 v10, v158, v10
	v_add_f32_e32 v11, v159, v11
	v_exp_f32_e32 v203, v69
	v_add_f32_e32 v10, v164, v10
	v_add_f32_e32 v11, v165, v11
	v_mfma_f32_16x16x32_bf16 v[2:5], v[218:221], v[2:5], v[14:17]
	v_add_f32_e64 v10, v162, v10
	v_add_f32_e64 v11, v163, v11
	v_cvt_pk_bf16_f32 v12, v159, v165
	v_add_f32_e32 v10, v170, v10
	v_add_f32_e32 v11, v171, v11
	v_cvt_pk_bf16_f32 v13, v163, v171
	v_add_f32_e32 v10, v76, v10
	v_add_f32_e32 v11, v77, v11
	v_cvt_pk_bf16_f32 v14, v197, v199
	v_add_f32_e32 v10, v80, v10
	v_add_f32_e32 v11, v81, v11
	v_cvt_pk_bf16_f32 v15, v189, v193
	v_add_f32_e32 v10, v78, v10
	v_add_f32_e32 v11, v79, v11
	v_cvt_pk_bf16_f32 v16, v191, v195
	v_add_f32_e32 v10, v84, v10
	v_add_f32_e32 v11, v85, v11
	v_cvt_pk_bf16_f32 v17, v201, v203
	v_add_f32_e32 v10, v82, v10
	v_add_f32_e32 v11, v83, v11
	v_exp_f32_e32 v187, v58
	v_add_f32_e32 v10, v88, v10
	v_add_f32_e32 v11, v89, v11
	v_exp_f32_e32 v179, v59
	v_add_f32_e32 v10, v86, v10
	v_add_f32_e32 v11, v87, v11
	v_exp_f32_e32 v177, v60
	v_add_f32_e32 v10, v96, v10
	v_add_f32_e32 v11, v97, v11
	v_exp_f32_e32 v181, v61
	v_add_f32_e32 v10, v70, v10
	v_add_f32_e32 v11, v71, v11
	v_exp_f32_e32 v175, v228
	v_add_f32_e32 v10, v72, v10
	v_add_f32_e32 v11, v73, v11
	v_exp_f32_e32 v119, v229
	v_add_f32_e32 v10, v74, v10
	v_add_f32_e32 v11, v75, v11
	v_exp_f32_e32 v129, v230
	v_add_f32_e32 v10, v94, v10
	v_add_f32_e32 v11, v95, v11
	v_exp_f32_e32 v185, v231
	v_add_f32_e32 v6, v92, v10
	v_add_f32_e32 v7, v93, v11
	v_exp_f32_e32 v183, v18
	v_add_f32_e32 v6, v100, v6
	v_add_f32_e32 v7, v101, v7
	v_exp_f32_e32 v169, v19
	v_add_f32_e32 v6, v116, v6
	v_add_f32_e32 v7, v117, v7
	v_exp_f32_e32 v167, v20
	v_add_f32_e32 v6, v126, v6
	v_add_f32_e32 v7, v127, v7
	v_exp_f32_e32 v173, v21
	v_add_f32_e32 v6, v90, v6
	v_add_f32_e32 v7, v91, v7
	v_exp_f32_e32 v105, v150
	v_add_f32_e32 v6, v98, v6
	v_add_f32_e32 v7, v99, v7
	v_exp_f32_e32 v107, v152
	v_add_f32_e32 v6, v114, v6
	v_add_f32_e32 v7, v115, v7
	v_exp_f32_e32 v141, v153
	v_add_f32_e32 v6, v124, v6
	v_add_f32_e32 v7, v125, v7
	v_exp_f32_e32 v137, v146
	v_add_f32_e32 v6, v122, v6
	v_add_f32_e32 v7, v123, v7
	v_exp_f32_e32 v135, v147
	v_add_f32_e32 v6, v130, v6
	v_add_f32_e32 v7, v131, v7
	v_exp_f32_e32 v139, v148
	v_add_f32_e32 v6, v132, v6
	v_add_f32_e32 v7, v133, v7
	v_exp_f32_e32 v111, v149
	v_add_f32_e32 v6, v0, v6
	v_add_f32_e32 v7, v1, v7
	v_exp_f32_e32 v109, v2
	v_add_f32_e32 v70, v6, v7
	v_add_f32_e32 v6, v196, v222
	v_add_f32_e32 v7, v197, v223
	v_mov_b32_e32 v222, v103
	v_add_f32_e32 v6, v198, v6
	v_add_f32_e32 v7, v199, v7
	v_exp_f32_e32 v103, v151
	v_add_f32_e32 v6, v188, v6
	v_add_f32_e32 v7, v189, v7
	v_exp_f32_e32 v121, v3
	v_add_f32_e32 v6, v192, v6
	v_add_f32_e32 v7, v193, v7
	v_exp_f32_e32 v113, v4
	v_add_f32_e32 v6, v190, v6
	v_add_f32_e32 v7, v191, v7
	v_add_f32_e32 v10, v194, v6
	v_add_f32_e32 v11, v195, v7
	ds_read_b64_tr_b16 v[8:9], v226 offset:35072
	ds_read_b64_tr_b16 v[6:7], v226 offset:32768
	ds_read_b64_tr_b16 v[54:55], v226 offset:32800
	ds_read_b64_tr_b16 v[56:57], v226 offset:35104
	v_add_f32_e32 v62, v200, v10
	v_add_f32_e32 v63, v201, v11
	v_cvt_pk_bf16_f32 v10, v143, v157
	v_cvt_pk_bf16_f32 v11, v145, v161
	s_waitcnt lgkmcnt(0)
	v_mfma_f32_16x16x32_bf16 v[42:45], v[54:57], v[14:17], v[42:45]
	v_add_f32_e64 v62, v202, v62
	v_add_f32_e64 v63, v203, v63
	v_add_f32_e32 v62, v186, v62
	v_add_f32_e32 v63, v187, v63
	v_mfma_f32_16x16x32_bf16 v[46:49], v[6:9], v[10:13], v[46:49]
	v_mfma_f32_16x16x32_bf16 v[6:9], v[6:9], v[14:17], v[50:53]
	s_nop 2
	ds_read_b64_tr_b16 v[50:51], v226 offset:32832
	ds_read_b64_tr_b16 v[52:53], v226 offset:35136
	v_mfma_f32_16x16x32_bf16 v[38:41], v[54:57], v[10:13], v[38:41]
	ds_read_b64_tr_b16 v[54:55], v226 offset:32864
	ds_read_b64_tr_b16 v[56:57], v226 offset:35168
	s_waitcnt lgkmcnt(2)
	v_mfma_f32_16x16x32_bf16 v[22:25], v[50:53], v[10:13], v[22:25]
	v_mfma_f32_16x16x32_bf16 v[34:37], v[50:53], v[14:17], v[34:37]
	v_cvt_pk_bf16_f32 v50, v187, v179
	v_cvt_pk_bf16_f32 v51, v177, v181
	v_cvt_pk_bf16_f32 v52, v175, v119
	s_waitcnt lgkmcnt(0)
	v_mfma_f32_16x16x32_bf16 v[10:13], v[54:57], v[10:13], v[30:33]
	s_nop 2
	ds_read_b64_tr_b16 v[30:31], v226 offset:37376
	ds_read_b64_tr_b16 v[32:33], v226 offset:39680
	v_cvt_pk_bf16_f32 v53, v129, v185
	v_mfma_f32_16x16x32_bf16 v[14:17], v[54:57], v[14:17], v[26:29]
	ds_read_b64_tr_b16 v[54:55], v226 offset:37408
	ds_read_b64_tr_b16 v[56:57], v226 offset:39712
	ds_read_b64_tr_b16 v[18:19], v226 offset:37440
	ds_read_b64_tr_b16 v[20:21], v226 offset:39744
	v_cvt_pk_bf16_f32 v26, v77, v81
	v_cvt_pk_bf16_f32 v27, v79, v85
	v_cvt_pk_bf16_f32 v28, v83, v89
	v_cvt_pk_bf16_f32 v29, v87, v97
	s_waitcnt lgkmcnt(4)
	v_mfma_f32_16x16x32_bf16 v[6:9], v[30:33], v[50:53], v[6:9]
	v_mfma_f32_16x16x32_bf16 v[46:49], v[30:33], v[26:29], v[46:49]
	s_waitcnt lgkmcnt(2)
; #define LASP __attribute__((address_space(3)))
; template <int DQK>
; __device__ __forceinline__ void flash_item(unsigned char* smem, const bf16_t* Q, int qs, const bf16_t* K0, const bf16_t* V0, int n0, const bf16_t* K1, const bf16_t* V1, int n1, int ks, int vs, bf16_t* Oo, int os, float shift) {
;     ...
;         for (int qg = 0; qg < 2; ++qg) {
;             float ps = 0.f;
; #pragma unroll
;             for (int kg = 0; kg < NKG; ++kg)
; #pragma unroll
;                 for (int j = 0; j < 4; ++j) { const float p = __builtin_amdgcn_exp2f(s[kg][qg][j]); s[kg][qg][j] = p; ps += p; }
;             lsum[qg] += ps;
;         }
; #pragma unroll
;         for (int kp = 0; kp < NKP; ++kp) {
;             bf16x8_t pb[2];
; #pragma unroll
;             for (int qg = 0; qg < 2; ++qg) {
;                 const f32x4_t a = s[2 * kp][qg], b = s[2 * kp + 1][qg];
;                 u32x4_t pk; pk.x = pg8::cvt_pk_bf16(a[0], a[1]); pk.y = pg8::cvt_pk_bf16(a[2], a[3]); pk.z = pg8::cvt_pk_bf16(b[0], b[1]); pk.w = pg8::cvt_pk_bf16(b[2], b[3]);
;                 pb[qg] = __builtin_bit_cast(bf16x8_t, pk);
;             }
; #pragma unroll
;             for (int dg = 0; dg < 4; ++dg) {
;                 LASP unsigned char* va = ls + VOFF + (32 * kp + 4 * fq + (fr >> 2)) * VR + (16 * dg + 4 * (fr & 3)) * 2;
;                 const s16x4 v0 = __builtin_amdgcn_ds_read_tr16_b64_v4i16((LASP s16x4*)va);
;                 const s16x4 v1 = __builtin_amdgcn_ds_read_tr16_b64_v4i16((LASP s16x4*)(va + 16 * VR));
;                 const bf16x8_t vf = __builtin_shufflevector(v0, v1, 0, 1, 2, 3, 4, 5, 6, 7);
;                 o[dg][0] = __builtin_amdgcn_mfma_f32_16x16x32_bf16(vf, pb[0], o[dg][0], 0, 0, 0);
;                 o[dg][1] = __builtin_amdgcn_mfma_f32_16x16x32_bf16(vf, pb[1], o[dg][1], 0, 0, 0);
;             }
;         }
;     }
;     ...
; #pragma unroll
;     for (int qg = 0; qg < 2; ++qg) {
;         float l = lsum[qg]; l += swz<16>(l); l = x32_sum(l);
;         const float inv = 1.0f / l;
;         bf16_t* orow = Oo + (size_t)(wave * 32 + qg * 16 + fr) * os + fq * 4;
; #pragma unroll
;         for (int dg = 0; dg < 4; ++dg) {
;             u32x2_t w; w.x = pg8::cvt_pk_bf16(o[dg][qg][0] * inv, o[dg][qg][1] * inv); w.y = pg8::cvt_pk_bf16(o[dg][qg][2] * inv, o[dg][qg][3] * inv);
;             *(u32x2_t*)(orow + dg * 16) = w;
;         }
	v_mfma_f32_16x16x32_bf16 v[30:33], v[54:57], v[26:29], v[38:41]
	s_nop 2
	v_add_f32_e64 v38, v178, v62
	v_add_f32_e64 v39, v179, v63
	s_waitcnt lgkmcnt(0)
	v_mfma_f32_16x16x32_bf16 v[22:25], v[18:21], v[26:29], v[22:25]
	v_add_f32_e64 v38, v176, v38
	v_add_f32_e64 v39, v177, v39
	v_add_f32_e32 v58, v180, v38
	v_add_f32_e32 v59, v181, v39
	v_mfma_f32_16x16x32_bf16 v[38:41], v[54:57], v[50:53], v[42:45]
	s_nop 2
	ds_read_b64_tr_b16 v[42:43], v226 offset:37472
	ds_read_b64_tr_b16 v[44:45], v226 offset:39776
	v_add_f32_e32 v54, v174, v58
	v_add_f32_e32 v55, v175, v59
	v_exp_f32_e32 v57, v5
	v_mfma_f32_16x16x32_bf16 v[18:21], v[18:21], v[50:53], v[34:37]
	v_add_f32_e64 v54, v118, v54
	v_add_f32_e64 v55, v119, v55
	v_mov_b32_e32 v56, v0
	v_add_f32_e32 v54, v128, v54
	v_add_f32_e32 v55, v129, v55
	s_waitcnt lgkmcnt(0)
	v_mfma_f32_16x16x32_bf16 v[10:13], v[42:45], v[26:29], v[10:13]
	ds_read_b64_tr_b16 v[26:27], v226 offset:41984
	ds_read_b64_tr_b16 v[28:29], v226 offset:44288
	v_cvt_pk_bf16_f32 v34, v71, v73
	v_cvt_pk_bf16_f32 v35, v75, v95
	v_mfma_f32_16x16x32_bf16 v[14:17], v[42:45], v[50:53], v[14:17]
	ds_read_b64_tr_b16 v[50:51], v226 offset:42016
	ds_read_b64_tr_b16 v[52:53], v226 offset:44320
	v_cvt_pk_bf16_f32 v36, v93, v101
	v_cvt_pk_bf16_f32 v37, v117, v127
	v_cvt_pk_bf16_f32 v42, v183, v169
	v_cvt_pk_bf16_f32 v43, v167, v173
	v_cvt_pk_bf16_f32 v44, v105, v103
	v_cvt_pk_bf16_f32 v45, v107, v141
	s_waitcnt lgkmcnt(2)
	v_mfma_f32_16x16x32_bf16 v[46:49], v[26:29], v[34:37], v[46:49]
	v_add_f32_e64 v54, v184, v54
	v_add_f32_e64 v55, v185, v55
	v_add_f32_e32 v54, v182, v54
	v_add_f32_e32 v55, v183, v55
	v_mfma_f32_16x16x32_bf16 v[6:9], v[26:29], v[42:45], v[6:9]
	ds_read_b64_tr_b16 v[26:27], v226 offset:42048
	ds_read_b64_tr_b16 v[28:29], v226 offset:44352
	v_add_f32_e32 v54, v168, v54
	v_add_f32_e32 v55, v169, v55
	s_waitcnt lgkmcnt(2)
	v_mfma_f32_16x16x32_bf16 v[30:33], v[50:53], v[34:37], v[30:33]
	v_add_f32_e64 v54, v166, v54
	v_add_f32_e64 v55, v167, v55
	v_add_f32_e32 v54, v172, v54
	v_add_f32_e32 v55, v173, v55
	v_mfma_f32_16x16x32_bf16 v[38:41], v[50:53], v[42:45], v[38:41]
	ds_read_b64_tr_b16 v[50:51], v226 offset:42080
	ds_read_b64_tr_b16 v[52:53], v226 offset:44384
	ds_read_b64_tr_b16 v[2:3], v226 offset:46592
	ds_read_b64_tr_b16 v[4:5], v226 offset:48896
	s_waitcnt lgkmcnt(4)
	v_mfma_f32_16x16x32_bf16 v[22:25], v[26:29], v[34:37], v[22:25]
	v_mfma_f32_16x16x32_bf16 v[18:21], v[26:29], v[42:45], v[18:21]
	s_waitcnt lgkmcnt(2)
	v_mfma_f32_16x16x32_bf16 v[10:13], v[50:53], v[34:37], v[10:13]
	v_cvt_pk_bf16_f32 v34, v91, v99
	v_cvt_pk_bf16_f32 v35, v115, v125
	v_cvt_pk_bf16_f32 v36, v123, v131
	v_mfma_f32_16x16x32_bf16 v[26:29], v[50:53], v[42:45], v[14:17]
	v_cvt_pk_bf16_f32 v37, v133, v1
	v_cvt_pk_bf16_f32 v42, v137, v135
	ds_read_b64_tr_b16 v[50:51], v226 offset:46624
	ds_read_b64_tr_b16 v[52:53], v226 offset:48928
	v_cvt_pk_bf16_f32 v43, v139, v111
	v_cvt_pk_bf16_f32 v44, v109, v121
	v_cvt_pk_bf16_f32 v45, v113, v57
	s_waitcnt lgkmcnt(2)
	v_mfma_f32_16x16x32_bf16 v[46:49], v[2:5], v[34:37], v[46:49]
	ds_swizzle_b32 v1, v70 offset:swizzle(SWAP,16)
	s_waitcnt lgkmcnt(0)
	v_add_f32_e32 v1, v70, v1
	v_mfma_f32_16x16x32_bf16 v[14:17], v[2:5], v[42:45], v[6:9]
	v_add_f32_e64 v2, v104, v54
	v_add_f32_e64 v3, v105, v55
	s_nop 0
	ds_read_b64_tr_b16 v[6:7], v226 offset:46656
	ds_read_b64_tr_b16 v[8:9], v226 offset:48960
	v_add_f32_e32 v2, v102, v2
	v_add_f32_e32 v3, v103, v3
	v_mfma_f32_16x16x32_bf16 v[30:33], v[50:53], v[34:37], v[30:33]
	v_add_f32_e64 v2, v106, v2
	v_add_f32_e64 v3, v107, v3
	v_add_f32_e32 v54, v140, v2
	v_add_f32_e32 v55, v141, v3
	v_mfma_f32_16x16x32_bf16 v[2:5], v[50:53], v[42:45], v[38:41]
	s_nop 2
	v_add_f32_e64 v38, v136, v54
	v_add_f32_e64 v39, v137, v55
	s_waitcnt lgkmcnt(0)
	v_mfma_f32_16x16x32_bf16 v[22:25], v[6:9], v[34:37], v[22:25]
	v_add_f32_e64 v38, v134, v38
	v_add_f32_e64 v39, v135, v39
	v_add_f32_e32 v50, v138, v38
	v_add_f32_e32 v51, v139, v39
	ds_read_b64_tr_b16 v[38:39], v226 offset:46688
	ds_read_b64_tr_b16 v[40:41], v226 offset:48992
	v_add_f32_e32 v50, v110, v50
	v_add_f32_e32 v51, v111, v51
	v_mfma_f32_16x16x32_bf16 v[6:9], v[6:9], v[42:45], v[18:21]
	v_add_f32_e64 v50, v108, v50
	v_add_f32_e64 v51, v109, v51
	v_add_f32_e32 v50, v120, v50
	v_add_f32_e32 v51, v121, v51
	v_add_f32_e32 v18, v112, v50
	v_add_f32_e32 v19, v113, v51
	v_add_f32_e32 v50, v56, v18
	v_add_f32_e32 v51, v57, v19
	s_waitcnt lgkmcnt(0)
	v_mfma_f32_16x16x32_bf16 v[18:21], v[38:41], v[34:37], v[10:13]
	v_add_f32_e32 v50, v50, v51
	s_nop 1
	v_mov_b32_e32 v10, v1
	s_nop 1
	v_permlane32_swap_b32_e32 v1, v10
	v_add_f32_e32 v1, v1, v10
	v_div_scale_f32 v34, s[16:17], v1, v1, 1.0
	v_rcp_f32_e32 v35, v34
	v_mfma_f32_16x16x32_bf16 v[10:13], v[38:41], v[42:45], v[26:29]
	s_nop 2
	v_fma_f32 v28, -v34, v35, 1.0
	v_fmac_f32_e32 v35, v28, v35
	v_div_scale_f32 v28, vcc, 1.0, v1, 1.0
	v_mul_f32_e32 v29, v28, v35
	v_fma_f32 v36, -v34, v29, v28
	v_fmac_f32_e32 v29, v36, v35
	v_fma_f32 v28, -v34, v29, v28
	v_div_fmas_f32 v28, v28, v35, v29
	v_div_fixup_f32 v28, v28, v1, 1.0
	ds_swizzle_b32 v1, v50 offset:swizzle(SWAP,16)
	v_pk_mul_f32 v[18:19], v[18:19], v[28:29] op_sel_hi:[1,0]
	v_lshl_add_u64 v[26:27], s[2:3], 0, v[204:205]
	v_cvt_pk_bf16_f32 v18, v18, v19
	v_pk_mul_f32 v[22:23], v[22:23], v[28:29] op_sel_hi:[1,0]
	s_waitcnt lgkmcnt(0)
	v_add_f32_e32 v1, v50, v1
	v_mov_b32_e32 v19, v1
	v_pk_mul_f32 v[24:25], v[24:25], v[28:29] op_sel_hi:[1,0]
	s_nop 0
	v_permlane32_swap_b32_e32 v1, v19
	v_mad_i64_i32 v[34:35], s[2:3], v211, s93, v[26:27]
	v_cvt_pk_bf16_f32 v22, v22, v23
	v_cvt_pk_bf16_f32 v23, v24, v25
	v_add_f32_e32 v1, v1, v19
	global_store_dwordx2 v[34:35], v[22:23], off offset:64
	v_div_scale_f32 v22, s[2:3], v1, v1, 1.0
	v_rcp_f32_e32 v23, v22
	v_pk_mul_f32 v[20:21], v[20:21], v[28:29] op_sel_hi:[1,0]
	v_pk_mul_f32 v[36:37], v[46:47], v[28:29] op_sel_hi:[1,0]
	v_cvt_pk_bf16_f32 v19, v20, v21
	global_store_dwordx2 v[34:35], v[18:19], off offset:96
	v_fma_f32 v18, -v22, v23, 1.0
	v_fmac_f32_e32 v23, v18, v23
	v_div_scale_f32 v18, vcc, 1.0, v1, 1.0
	v_mul_f32_e32 v19, v18, v23
	v_fma_f32 v20, -v22, v19, v18
	v_fmac_f32_e32 v19, v20, v23
	v_fma_f32 v18, -v22, v19, v18
	v_div_fmas_f32 v18, v18, v23, v19
	v_div_fixup_f32 v18, v18, v1, 1.0
	v_pk_mul_f32 v[38:39], v[48:49], v[28:29] op_sel_hi:[1,0]
	v_pk_mul_f32 v[30:31], v[30:31], v[28:29] op_sel_hi:[1,0]
	v_pk_mul_f32 v[32:33], v[32:33], v[28:29] op_sel_hi:[1,0]
	v_pk_mul_f32 v[14:15], v[14:15], v[18:19] op_sel_hi:[1,0]
	v_pk_mul_f32 v[16:17], v[16:17], v[18:19] op_sel_hi:[1,0]
	v_mov_b32_e32 v211, v216
	v_cvt_pk_bf16_f32 v36, v36, v37
	v_cvt_pk_bf16_f32 v37, v38, v39
	v_cvt_pk_bf16_f32 v30, v30, v31
	v_cvt_pk_bf16_f32 v31, v32, v33
	v_mad_i64_i32 v[20:21], s[2:3], v227, s93, v[26:27]
	v_cvt_pk_bf16_f32 v14, v14, v15
	v_cvt_pk_bf16_f32 v15, v16, v17
	global_store_dwordx2 v[34:35], v[36:37], off
	global_store_dwordx2 v[34:35], v[30:31], off offset:32
	global_store_dwordx2 v[20:21], v[14:15], off

; #define LASP __attribute__((address_space(3)))
; __device__ __forceinline__ void na_item(unsigned char* smem, const bf16_t* U, const float* rpb_l, bf16_t* O, int b, int rp, int hp, float shift) {
;     ...
;         LASP unsigned char* base = ls + (i & 1) * BUF + hh * HSZ;
;         const bool hasctx = i < 8, latA = i < 8, latB = (i >= dB);
;         f32x4_t sA[4], sB[4];
; #pragma unroll
;         for (int g = 0; g < 4; ++g) { sA[g] = (f32x4_t){nsh, nsh, nsh, nsh}; sB[g] = (f32x4_t){nsh, nsh, nsh, nsh}; }
; #pragma unroll
;         for (int kk = 0; kk < 2; ++kk) {
; #pragma unroll
;             for (int g = 0; g < 2; ++g) {
;                 const bf16x8_t kl = *(const LASP bf16x8_t*)(base + (kcol0 + 16 * g + fr) * KR + (kk * 32 + fq * 8) * 2);
;                 sA[g] = __builtin_amdgcn_mfma_f32_16x16x32_bf16(kl, qfA[kk], sA[g], 0, 0, 0);
;                 sB[g] = __builtin_amdgcn_mfma_f32_16x16x32_bf16(kl, qfB[kk], sB[g], 0, 0, 0);
;                 const bf16x8_t kc = *(const LASP bf16x8_t*)(base + O_KC + (16 * g + fr) * KR + (kk * 32 + fq * 8) * 2);
;                 sA[2 + g] = __builtin_amdgcn_mfma_f32_16x16x32_bf16(kc, qfA[kk], sA[2 + g], 0, 0, 0);
;                 sB[2 + g] = __builtin_amdgcn_mfma_f32_16x16x32_bf16(kc, qfB[kk], sB[2 + g], 0, 0, 0);
;             }
;         }
;         const int relA = rsA + i - rA + 7, relB = relA - 1;
;         const int brA = min(max(relA, 0), 14), brB = min(max(relB, 0), 14);
; #pragma unroll
;         for (int g = 0; g < 2; ++g)
; #pragma unroll
;             for (int j = 0; j < 4; ++j) {
;                 const int kc = kcol0 + 16 * g + 4 * fq + j;
;                 const bool valid = (kc >= cs) && (kc < cs + 16);
;                 const int idx = min(max(kc - qc + 15, 0), 30);
;                 sA[g][j] = (valid && latA) ? sA[g][j] + bias[(hh * 15 + brA) * 32 + idx] : -INFINITY;
;                 sB[g][j] = (valid && latB) ? sB[g][j] + bias[(hh * 15 + brB) * 32 + idx] : -INFINITY;
;             }
.LBB0_859:
	s_bitcmp1_b32 s78, 0
	s_cselect_b32 s18, 0xd800, 0
	v_add_u32_e32 v111, s18, v121
	v_add_u32_e32 v86, v111, v108
	v_add_u32_e32 v144, v86, v126
	ds_read_b128 v[164:167], v144 offset:2304
	ds_read_b128 v[168:171], v144
	v_mov_b64_e32 v[80:81], s[62:63]
	v_mov_b64_e32 v[78:79], s[60:61]
	v_add_u32_e32 v145, v86, v127
	ds_read_b128 v[172:175], v145 offset:18432
	ds_read_b128 v[176:179], v145 offset:20736
	ds_read_b128 v[200:203], v144 offset:64
	ds_read_b128 v[204:207], v145 offset:18496
	s_cmp_lt_u32 s78, 8
	s_cselect_b64 vcc, -1, 0
	s_add_i32 s79, s97, s78
	ds_read_b128 v[212:215], v144 offset:2368
	s_waitcnt lgkmcnt(6)
	v_mfma_f32_16x16x32_bf16 v[136:139], v[164:167], v[14:17], v[78:81]
	s_max_i32 s18, s79, -7
	s_add_i32 s18, s18, 7
	s_min_u32 s18, s18, 14
	v_mfma_f32_16x16x32_bf16 v[140:143], v[164:167], v[22:25], v[78:81]
	ds_read_b128 v[164:167], v145 offset:20800
	s_waitcnt lgkmcnt(6)
	v_mfma_f32_16x16x32_bf16 v[82:85], v[168:171], v[14:17], v[78:81]
	v_mfma_f32_16x16x32_bf16 v[74:77], v[168:171], v[22:25], v[78:81]
	s_waitcnt lgkmcnt(5)
	v_mfma_f32_16x16x32_bf16 v[90:93], v[172:175], v[14:17], v[78:81]
	v_mfma_f32_16x16x32_bf16 v[86:89], v[172:175], v[22:25], v[78:81]
	s_waitcnt lgkmcnt(4)
	v_mfma_f32_16x16x32_bf16 v[156:159], v[176:179], v[14:17], v[78:81]
	v_mfma_f32_16x16x32_bf16 v[160:163], v[176:179], v[22:25], v[78:81]
	s_nop 2
	s_waitcnt lgkmcnt(3)
	v_mfma_f32_16x16x32_bf16 v[102:105], v[200:203], v[18:21], v[82:85]
	s_nop 2
	v_mfma_f32_16x16x32_bf16 v[98:101], v[200:203], v[26:29], v[74:77]
	s_waitcnt lgkmcnt(2)
	v_mfma_f32_16x16x32_bf16 v[74:77], v[204:207], v[18:21], v[90:93]
	v_mfma_f32_16x16x32_bf16 v[78:81], v[204:207], v[26:29], v[86:89]
	s_nop 2
	s_waitcnt lgkmcnt(1)
	v_mfma_f32_16x16x32_bf16 v[94:97], v[212:215], v[18:21], v[136:139]
	v_mfma_f32_16x16x32_bf16 v[90:93], v[212:215], v[26:29], v[140:143]
	s_nop 1
	v_add_u32_e32 v136, s18, v122
	v_lshl_add_u32 v138, v136, 7, s4
	s_waitcnt lgkmcnt(0)
	v_mfma_f32_16x16x32_bf16 v[82:85], v[164:167], v[18:21], v[156:159]
	s_cmp_ge_i32 s78, s5
	s_cselect_b64 s[76:77], -1, 0
	s_max_i32 s18, s79, -6
	s_add_i32 s18, s18, 6
	s_min_u32 s18, s18, 14
	v_mfma_f32_16x16x32_bf16 v[86:89], v[164:167], v[26:29], v[160:163]
	v_add_u32_e32 v139, s18, v122
	v_lshl_add_u32 v139, v139, 7, s4
	v_lshl_add_u32 v196, v128, 2, v138
	ds_read_b32 v180, v196
	v_lshl_add_u32 v197, v128, 2, v139
	ds_read_b32 v181, v197
	v_lshl_add_u32 v196, v129, 2, v138
	ds_read_b32 v182, v196
	v_lshl_add_u32 v197, v129, 2, v139
	ds_read_b32 v183, v197
	v_lshl_add_u32 v196, v130, 2, v138
	ds_read_b32 v184, v196
	v_lshl_add_u32 v197, v130, 2, v139
	ds_read_b32 v185, v197
	v_lshl_add_u32 v196, v131, 2, v138
	ds_read_b32 v186, v196
	v_lshl_add_u32 v197, v131, 2, v139
	ds_read_b32 v187, v197
	v_lshl_add_u32 v196, v132, 2, v138
	ds_read_b32 v188, v196
	v_lshl_add_u32 v197, v132, 2, v139
	ds_read_b32 v189, v197
	v_lshl_add_u32 v196, v133, 2, v138
	ds_read_b32 v190, v196
	v_lshl_add_u32 v197, v133, 2, v139
	ds_read_b32 v191, v197
	v_lshl_add_u32 v196, v134, 2, v138
	ds_read_b32 v192, v196
	v_lshl_add_u32 v197, v134, 2, v139
	ds_read_b32 v193, v197
	s_waitcnt lgkmcnt(12)
	s_and_b64 s[18:19], s[20:21], vcc
	v_add_f32_e32 v180, v102, v180
	v_cndmask_b32_e64 v137, v154, v180, s[18:19]
	s_and_b64 s[18:19], s[20:21], s[76:77]
	v_add_f32_e32 v181, v98, v181
	v_cndmask_b32_e64 v136, v154, v181, s[18:19]
	v_lshl_add_u32 v196, v135, 2, v138
	ds_read_b32 v194, v196
	v_lshl_add_u32 v197, v135, 2, v139
	ds_read_b32 v195, v197
	s_waitcnt lgkmcnt(12)
	s_and_b64 s[18:19], s[40:41], vcc
	v_add_f32_e32 v182, v103, v182
	v_cndmask_b32_e64 v102, v154, v182, s[18:19]
	s_and_b64 s[18:19], s[40:41], s[76:77]
	v_add_f32_e32 v183, v99, v183
	v_cndmask_b32_e64 v98, v154, v183, s[18:19]
	s_waitcnt lgkmcnt(10)
	s_and_b64 s[18:19], s[16:17], vcc
	v_add_f32_e32 v184, v104, v184
	v_cndmask_b32_e64 v103, v154, v184, s[18:19]
	s_and_b64 s[18:19], s[16:17], s[76:77]
	v_add_f32_e32 v185, v100, v185
	v_cndmask_b32_e64 v99, v154, v185, s[18:19]
	s_waitcnt lgkmcnt(8)
	s_and_b64 s[18:19], s[2:3], vcc
	v_add_f32_e32 v186, v105, v186
	v_cndmask_b32_e64 v104, v154, v186, s[18:19]
	s_and_b64 s[18:19], s[2:3], s[76:77]
	v_add_f32_e32 v187, v101, v187
	v_cndmask_b32_e64 v100, v154, v187, s[18:19]
	s_waitcnt lgkmcnt(6)
	s_and_b64 s[18:19], s[26:27], vcc
	v_add_f32_e32 v188, v94, v188
	v_cndmask_b32_e64 v105, v154, v188, s[18:19]
	s_and_b64 s[18:19], s[26:27], s[76:77]
	v_add_f32_e32 v189, v90, v189
	v_cndmask_b32_e64 v101, v154, v189, s[18:19]
	s_waitcnt lgkmcnt(4)
	s_and_b64 s[18:19], s[74:75], vcc
	v_add_f32_e32 v190, v95, v190
	v_cndmask_b32_e64 v140, v154, v190, s[18:19]
	s_and_b64 s[18:19], s[74:75], s[76:77]
	v_add_f32_e32 v191, v91, v191
	v_cndmask_b32_e64 v94, v154, v191, s[18:19]
	s_waitcnt lgkmcnt(2)
	s_and_b64 s[18:19], s[52:53], vcc
	v_add_f32_e32 v192, v96, v192
	v_cndmask_b32_e64 v91, v154, v192, s[18:19]
	s_and_b64 s[18:19], s[52:53], s[76:77]
	v_add_f32_e32 v193, v92, v193
	v_cndmask_b32_e64 v90, v154, v193, s[18:19]
	s_waitcnt lgkmcnt(0)
; #define LASP __attribute__((address_space(3)))
; __device__ __forceinline__ void na_item(unsigned char* smem, const bf16_t* U, const float* rpb_l, bf16_t* O, int b, int rp, int hp, float shift) {
;     ...
;         if (!hasctx) {
; #pragma unroll
;             for (int g = 2; g < 4; ++g) { sA[g] = (f32x4_t){-INFINITY, -INFINITY, -INFINITY, -INFINITY}; sB[g] = sA[g]; }
;         }
;         { float psA = 0.f, psB = 0.f;
; #pragma unroll
;           for (int g = 0; g < 4; ++g)
; #pragma unroll
;               for (int j = 0; j < 4; ++j) { const float pa = __builtin_amdgcn_exp2f(sA[g][j]); sA[g][j] = pa; psA += pa;
;                                             const float pb_ = __builtin_amdgcn_exp2f(sB[g][j]); sB[g][j] = pb_; psB += pb_; }
;           lA += psA; lB += psB; }
; #pragma unroll
;         for (int kp = 0; kp < 2; ++kp) {
;             u32x4_t pk;
;             pk.x = pg8::cvt_pk_bf16(sA[2 * kp][0], sA[2 * kp][1]); pk.y = pg8::cvt_pk_bf16(sA[2 * kp][2], sA[2 * kp][3]); pk.z = pg8::cvt_pk_bf16(sA[2 * kp + 1][0], sA[2 * kp + 1][1]); pk.w = pg8::cvt_pk_bf16(sA[2 * kp + 1][2], sA[2 * kp + 1][3]);
;             const bf16x8_t pbA = __builtin_bit_cast(bf16x8_t, pk);
;             pk.x = pg8::cvt_pk_bf16(sB[2 * kp][0], sB[2 * kp][1]); pk.y = pg8::cvt_pk_bf16(sB[2 * kp][2], sB[2 * kp][3]); pk.z = pg8::cvt_pk_bf16(sB[2 * kp + 1][0], sB[2 * kp + 1][1]); pk.w = pg8::cvt_pk_bf16(sB[2 * kp + 1][2], sB[2 * kp + 1][3]);
;             const bf16x8_t pbB = __builtin_bit_cast(bf16x8_t, pk);
;             LASP unsigned char* vb = kp == 0 ? base + O_VL + (kcol0 + 4 * fq + (fr >> 2)) * KR : base + O_VC + (4 * fq + (fr >> 2)) * KR;
; #pragma unroll
;             for (int dg = 0; dg < 4; ++dg) {
;                 LASP unsigned char* va = vb + (16 * dg + 4 * (fr & 3)) * 2;
;                 const s16x4 v0 = __builtin_amdgcn_ds_read_tr16_b64_v4i16((LASP s16x4*)va);
;                 const s16x4 v1 = __builtin_amdgcn_ds_read_tr16_b64_v4i16((LASP s16x4*)(va + 16 * KR));
;                 const bf16x8_t vf = __builtin_shufflevector(v0, v1, 0, 1, 2, 3, 4, 5, 6, 7);
;                 oA[dg] = __builtin_amdgcn_mfma_f32_16x16x32_bf16(vf, pbA, oA[dg], 0, 0, 0);
;                 oB[dg] = __builtin_amdgcn_mfma_f32_16x16x32_bf16(vf, pbB, oB[dg], 0, 0, 0);
;             }
;         }
;         __syncthreads();
;     }
	s_and_b64 s[18:19], s[38:39], vcc
	v_add_f32_e32 v194, v97, v194
	v_cndmask_b32_e64 v96, v154, v194, s[18:19]
	s_and_b64 s[18:19], s[38:39], s[76:77]
	v_add_f32_e32 v195, v93, v195
	v_cndmask_b32_e64 v92, v154, v195, s[18:19]
	s_mov_b64 s[76:77], exec
	s_mov_b64 s[78:79], exec
	v_add3_u32 v198, v111, v125, v123
	ds_read_b64_tr_b16 v[166:167], v198 offset:11520
	ds_read_b64_tr_b16 v[164:165], v198 offset:9216
	ds_read_b64_tr_b16 v[168:169], v198 offset:9280
	ds_read_b64_tr_b16 v[170:171], v198 offset:11584
	ds_read_b64_tr_b16 v[172:173], v198 offset:9248
	ds_read_b64_tr_b16 v[174:175], v198 offset:11552
	ds_read_b64_tr_b16 v[176:177], v198 offset:9312
	ds_read_b64_tr_b16 v[178:179], v198 offset:11616
	v_add3_u32 v199, v111, v124, v123
	ds_read_b64_tr_b16 v[182:183], v199 offset:25344
	ds_read_b64_tr_b16 v[180:181], v199 offset:23040
	ds_read_b64_tr_b16 v[184:185], v199 offset:23104
	ds_read_b64_tr_b16 v[186:187], v199 offset:25408
	v_exp_f32_e32 v137, v137
	v_exp_f32_e32 v136, v136
	v_exp_f32_e32 v139, v102
	v_exp_f32_e32 v138, v98
	v_exp_f32_e32 v103, v103
	v_exp_f32_e32 v102, v99
	v_exp_f32_e32 v143, v104
	v_exp_f32_e32 v142, v100
	v_cndmask_b32_e32 v148, v154, v84, vcc
	v_cndmask_b32_e32 v149, v154, v83, vcc
	v_cndmask_b32_e32 v83, v154, v75, vcc
	v_cndmask_b32_e32 v84, v154, v74, vcc
	v_exp_f32_e32 v105, v105
	v_exp_f32_e32 v104, v101
	v_exp_f32_e32 v141, v140
	v_exp_f32_e32 v140, v94
	v_add_f32_e32 v74, 0, v136
	v_add_f32_e32 v75, 0, v137
	v_exp_f32_e32 v95, v91
	v_add_f32_e32 v74, v138, v74
	v_add_f32_e32 v75, v139, v75
	v_exp_f32_e32 v94, v90
	v_add_f32_e32 v74, v102, v74
	v_add_f32_e32 v75, v103, v75
	v_exp_f32_e32 v93, v96
	v_add_f32_e32 v74, v142, v74
	v_add_f32_e32 v75, v143, v75
	v_exp_f32_e32 v92, v92
	v_add_f32_e32 v74, v104, v74
	v_add_f32_e32 v75, v105, v75
	v_cvt_pk_bf16_f32 v101, v102, v142
	v_cvt_pk_bf16_f32 v102, v104, v140
	v_add_f32_e32 v74, v140, v74
	v_add_f32_e32 v75, v141, v75
	v_cvt_pk_bf16_f32 v96, v137, v139
	v_cvt_pk_bf16_f32 v98, v105, v141
	v_cvt_pk_bf16_f32 v100, v136, v138
	v_cndmask_b32_e32 v97, v154, v89, vcc
	v_cndmask_b32_e32 v76, v154, v76, vcc
	v_cndmask_b32_e32 v145, v154, v87, vcc
	v_exp_f32_e32 v87, v76
	v_exp_f32_e32 v76, v97
	v_cvt_pk_bf16_f32 v97, v103, v143
	v_cvt_pk_bf16_f32 v99, v95, v93
	v_cvt_pk_bf16_f32 v103, v94, v92
	ds_read_b64_tr_b16 v[188:189], v199 offset:23072
	ds_read_b64_tr_b16 v[190:191], v199 offset:25376
	s_waitcnt lgkmcnt(12)
	v_mfma_f32_16x16x32_bf16 v[70:73], v[164:167], v[96:99], v[70:73]
	v_cndmask_b32_e32 v144, v154, v88, vcc
	v_cndmask_b32_e32 v146, v154, v86, vcc
	v_cndmask_b32_e32 v81, v154, v81, vcc
	v_mfma_f32_16x16x32_bf16 v[54:57], v[164:167], v[100:103], v[54:57]
	v_cndmask_b32_e32 v80, v154, v80, vcc
	v_cndmask_b32_e32 v79, v154, v79, vcc
	ds_read_b64_tr_b16 v[164:165], v199 offset:23136
	ds_read_b64_tr_b16 v[166:167], v199 offset:25440
	s_waitcnt lgkmcnt(12)
	v_mfma_f32_16x16x32_bf16 v[62:65], v[168:171], v[96:99], v[62:65]
	v_cndmask_b32_e32 v78, v154, v78, vcc
	v_cndmask_b32_e32 v147, v154, v85, vcc
	v_cndmask_b32_e32 v82, v154, v82, vcc
	v_mfma_f32_16x16x32_bf16 v[6:9], v[168:171], v[100:103], v[6:9]
	v_cndmask_b32_e32 v77, v154, v77, vcc
	v_exp_f32_e32 v91, v84
	v_exp_f32_e32 v90, v78
	v_exp_f32_e32 v89, v83
	v_exp_f32_e32 v88, v79
	v_exp_f32_e32 v86, v80
	v_exp_f32_e32 v85, v77
	v_exp_f32_e32 v84, v81
	v_exp_f32_e32 v83, v82
	v_exp_f32_e32 v82, v146
	v_exp_f32_e32 v81, v149
	v_exp_f32_e32 v80, v145
	v_exp_f32_e32 v79, v148
	v_exp_f32_e32 v78, v144
	v_exp_f32_e32 v77, v147
	s_waitcnt lgkmcnt(10)
	v_mfma_f32_16x16x32_bf16 v[66:69], v[172:175], v[96:99], v[66:69]
	v_add_f32_e64 v74, v94, v74
	v_add_f32_e64 v75, v95, v75
	v_lshl_add_u64 v[114:115], v[114:115], 0, s[14:15]
	v_add_f32_e32 v74, v92, v74
	v_add_f32_e32 v75, v93, v75
	v_mfma_f32_16x16x32_bf16 v[2:5], v[172:175], v[100:103], v[2:5]
	v_add_f32_e64 v74, v90, v74
	v_add_f32_e64 v75, v91, v75
	v_lshl_add_u64 v[116:117], v[116:117], 0, s[34:35]
	v_add_f32_e32 v74, v88, v74
	v_add_f32_e32 v75, v89, v75
	s_waitcnt lgkmcnt(8)
	v_mfma_f32_16x16x32_bf16 v[58:61], v[176:179], v[96:99], v[58:61]
	v_cvt_pk_bf16_f32 v96, v91, v89
	v_cvt_pk_bf16_f32 v97, v87, v85
	v_cvt_pk_bf16_f32 v98, v83, v81
	v_mfma_f32_16x16x32_bf16 v[10:13], v[176:179], v[100:103], v[10:13]
	v_cvt_pk_bf16_f32 v99, v79, v77
	v_cvt_pk_bf16_f32 v100, v90, v88
	v_cvt_pk_bf16_f32 v101, v86, v84
	v_cvt_pk_bf16_f32 v102, v82, v80
	v_cvt_pk_bf16_f32 v103, v78, v76
	s_waitcnt lgkmcnt(6)
	v_mfma_f32_16x16x32_bf16 v[70:73], v[180:183], v[96:99], v[70:73]
	v_add_f32_e32 v74, v86, v74
	v_add_f32_e32 v75, v87, v75
	s_andn2_b64 vcc, exec, s[28:29]
	v_mfma_f32_16x16x32_bf16 v[54:57], v[180:183], v[100:103], v[54:57]
	v_add_f32_e32 v74, v84, v74
	v_add_f32_e32 v75, v85, v75
	s_waitcnt lgkmcnt(4)
	v_mfma_f32_16x16x32_bf16 v[62:65], v[184:187], v[96:99], v[62:65]
	v_add_f32_e64 v74, v82, v74
	v_add_f32_e64 v75, v83, v75
	v_add_f32_e32 v74, v80, v74
	v_add_f32_e32 v75, v81, v75
	v_mfma_f32_16x16x32_bf16 v[6:9], v[184:187], v[100:103], v[6:9]
	v_add_f32_e32 v74, v78, v74
	v_add_f32_e32 v75, v79, v75
	s_waitcnt lgkmcnt(2)
	v_mfma_f32_16x16x32_bf16 v[66:69], v[188:191], v[96:99], v[66:69]
	v_add_f32_e64 v74, v76, v74
	v_add_f32_e64 v75, v77, v75
	s_waitcnt lgkmcnt(0)
	s_barrier
	v_add_f32_e32 v112, v112, v74
	v_add_f32_e32 v113, v113, v75
	v_mfma_f32_16x16x32_bf16 v[2:5], v[188:191], v[100:103], v[2:5]
	v_mfma_f32_16x16x32_bf16 v[58:61], v[164:167], v[96:99], v[58:61]
	v_mfma_f32_16x16x32_bf16 v[10:13], v[164:167], v[100:103], v[10:13]
	s_cbranch_vccz .LBB0_819
	s_mov_b32 s78, s54
	s_branch .LBB0_848
